# K-loops of P3/P4/P5/P6: the s_setprio 0 / s_setprio 1 flip pair between the two 16-MFMA halves of each 32-MFMA block deleted (priority stays 1 across the block)
# baseline (speedup 1.0000x reference)
; #define PG8_STAGE(bufoff, gbase, voff) do { _Pragma("unroll") for (int _i = 0; _i < 2; ++_i) { unsigned vo_ = (voff)[_i]; if constexpr (FP8) asm volatile("" : "+v"(vo_)); \
;         __builtin_amdgcn_global_load_lds((const unsigned*)((const char*)(gbase) + vo_), (PG8_LAS unsigned*)(lds + (bufoff) + ldsw + _i * 8192), 16, 0, 0); } } while (0)
; #define PG8_LDA(dst, b, h) do { _Pragma("unroll") for (int m = 0; m < 4; ++m) _Pragma("unroll") for (int k = 0; k < 2; ++k) dst[m][k] = *(const PG8_LAS bf16x8*)(lds + PG8_SA(b, h) + aoff + m * 2048 + k * 1024); } while (0)
; #define PG8_LDB(dst, b, h) do { _Pragma("unroll") for (int n = 0; n < 2; ++n) _Pragma("unroll") for (int k = 0; k < 2; ++k) dst[n][k] = *(const PG8_LAS bf16x8*)(lds + PG8_SB(b, h) + boff + n * 2048 + k * 1024); } while (0)
; #define PG8_WAIT_V(n) asm volatile("s_waitcnt vmcnt(" #n ")" ::: "memory")
; #define PG8_WAIT_L(n) asm volatile("s_waitcnt lgkmcnt(" #n ")" ::: "memory")
; #define PG8_BAR __builtin_amdgcn_s_barrier()
; #define PG8_SCHED __builtin_amdgcn_sched_barrier(0)
; template <class Epi, class Sched, bool ALIGN_EPI = false, bool SP2 = false, bool FP8 = false>
; __device__ __forceinline__ void gemm_phase(PG8_LAS unsigned char* lds, const Gemm g, const Sched& S, const Epi& E) {
;     ...
;             PG8_LDB(B0, 0, 0); PG8_LDB(B1, 0, 1); PG8_SCHED; PG8_LDA(At, 0, 0); PG8_STAGE(PG8_SA(1, 1), a1 + hstep, voffA);
;             PG8_WAIT_V(8); PG8_WAIT_L(0); PG8_BAR; PG8_MMA(0, 0, At, B0); PG8_MMA(0, 1, At, B1); PG8_BAR; PG8_SCHED;
;             PG8_LDA(At, 0, 1); PG8_STAGE(PG8_SB(0, 0), b2, voffB); PG8_STAGE(PG8_SB(0, 1), b2 + hstep, voffB); PG8_STAGE(PG8_SA(0, 0), a2, voffA);
;             PG8_WAIT_V(8); PG8_WAIT_L(0); PG8_BAR; PG8_MMA(1, 0, At, B0); PG8_MMA(1, 1, At, B1); PG8_BAR; PG8_SCHED;
.LBB0_305:
	s_add_u32 s52, s10, 0xfffe8080
	s_addc_u32 s53, s11, -1
	s_and_b64 s[0:1], s[62:63], exec
	s_cselect_b32 s65, s5, s53
	s_cselect_b32 s64, s4, s52
	s_add_i32 s52, 0, 0x10000
	v_add_u32_e32 v128, s52, v152
	ds_read_b128 v[134:137], v128
	ds_read_b128 v[138:141], v128 offset:1024
	ds_read_b128 v[156:159], v128 offset:2048
	ds_read_b128 v[160:163], v128 offset:3072
	v_add_u32_e32 v128, s84, v152
	ds_read_b128 v[164:167], v128
	ds_read_b128 v[168:171], v128 offset:1024
	ds_read_b128 v[178:181], v128 offset:2048
	ds_read_b128 v[182:185], v128 offset:3072
	s_and_b64 s[0:1], s[62:63], exec
	s_cselect_b32 s63, s61, s90
	s_cselect_b32 s62, s60, s89
	v_mov_b32_e32 v128, v146
	ds_read_b128 v[186:189], v153
	ds_read_b128 v[190:193], v153 offset:1024
	ds_read_b128 v[198:201], v153 offset:2048
	ds_read_b128 v[202:205], v153 offset:3072
	ds_read_b128 v[206:209], v153 offset:4096
	ds_read_b128 v[210:213], v153 offset:5120
	ds_read_b128 v[214:217], v153 offset:6144
	ds_read_b128 v[218:221], v153 offset:7168
	s_add_i32 m0, s68, 0xc000
	s_nop 0
	global_load_lds_dwordx4 v128, s[10:11]
	v_mov_b32_e32 v128, v148
	s_add_i32 m0, s68, 0xe000
	s_nop 0
	global_load_lds_dwordx4 v128, s[10:11]
	s_waitcnt vmcnt(8)
	s_waitcnt lgkmcnt(0)
	s_barrier
	s_setprio 1
	s_waitcnt lgkmcnt(0)
	v_mfma_scale_f32_16x16x128_f8f6f4 v[112:115], v[134:141], v[186:193], v[112:115], v154, v154 op_sel_hi:[0,0,0]
	v_mfma_scale_f32_16x16x128_f8f6f4 v[116:119], v[156:163], v[186:193], v[116:119], v154, v154 op_sel_hi:[0,0,0]
	v_mfma_scale_f32_16x16x128_f8f6f4 v[96:99], v[134:141], v[198:205], v[96:99], v154, v154 op_sel_hi:[0,0,0]
	v_mfma_scale_f32_16x16x128_f8f6f4 v[100:103], v[156:163], v[198:205], v[100:103], v154, v154 op_sel_hi:[0,0,0]
	v_mfma_scale_f32_16x16x128_f8f6f4 v[142:145], v[134:141], v[206:213], v[80:83], v154, v154 op_sel_hi:[0,0,0]
	v_mfma_scale_f32_16x16x128_f8f6f4 v[172:175], v[156:163], v[206:213], v[84:87], v154, v154 op_sel_hi:[0,0,0]
	v_mfma_scale_f32_16x16x128_f8f6f4 v[194:197], v[134:141], v[214:221], v[64:67], v154, v154 op_sel_hi:[0,0,0]
	v_mfma_scale_f32_16x16x128_f8f6f4 v[222:225], v[156:163], v[214:221], v[68:71], v154, v154 op_sel_hi:[0,0,0]
	v_mfma_scale_f32_16x16x128_f8f6f4 v[120:123], v[164:171], v[186:193], v[120:123], v154, v154 op_sel_hi:[0,0,0]
	v_mfma_scale_f32_16x16x128_f8f6f4 v[124:127], v[178:185], v[186:193], v[124:127], v154, v154 op_sel_hi:[0,0,0]
	v_mfma_scale_f32_16x16x128_f8f6f4 v[104:107], v[164:171], v[198:205], v[104:107], v154, v154 op_sel_hi:[0,0,0]
	v_mfma_scale_f32_16x16x128_f8f6f4 v[108:111], v[178:185], v[198:205], v[108:111], v154, v154 op_sel_hi:[0,0,0]
	v_mfma_scale_f32_16x16x128_f8f6f4 v[186:189], v[164:171], v[206:213], v[88:91], v154, v154 op_sel_hi:[0,0,0]
	v_mfma_scale_f32_16x16x128_f8f6f4 v[190:193], v[178:185], v[206:213], v[92:95], v154, v154 op_sel_hi:[0,0,0]
	v_mfma_scale_f32_16x16x128_f8f6f4 v[198:201], v[164:171], v[214:221], v[72:75], v154, v154 op_sel_hi:[0,0,0]
	v_mfma_scale_f32_16x16x128_f8f6f4 v[202:205], v[178:185], v[214:221], v[76:79], v154, v154 op_sel_hi:[0,0,0]
	s_setprio 0
	s_barrier
	v_mov_b32_e32 v128, v147
	s_add_i32 s0, s52, s66
	ds_read_b128 v[64:67], v153 offset:16384
	ds_read_b128 v[68:71], v153 offset:17408
	ds_read_b128 v[72:75], v153 offset:18432
	ds_read_b128 v[76:79], v153 offset:19456
	ds_read_b128 v[80:83], v153 offset:20480
	ds_read_b128 v[84:87], v153 offset:21504
	ds_read_b128 v[88:91], v153 offset:22528
	ds_read_b128 v[92:95], v153 offset:23552
	s_mov_b32 m0, s0
	s_nop 0
	global_load_lds_dwordx4 v128, s[62:63]
	v_mov_b32_e32 v128, v149
	s_add_i32 m0, s0, 0x2000
	s_add_u32 s0, s62, 0x18000
	global_load_lds_dwordx4 v128, s[62:63]
	s_addc_u32 s1, s63, 0
	v_mov_b32_e32 v128, v147
	s_add_i32 s52, s84, s66
	s_mov_b32 m0, s52
	s_nop 0
	global_load_lds_dwordx4 v128, s[0:1]
	v_mov_b32_e32 v128, v149
	s_add_i32 m0, s52, 0x2000
	s_nop 0
	global_load_lds_dwordx4 v128, s[0:1]
	v_mov_b32_e32 v128, v146
	s_mov_b32 m0, s68
	s_nop 0
	global_load_lds_dwordx4 v128, s[64:65]
	v_mov_b32_e32 v128, v148
	s_mov_b32 m0, s69
	s_nop 0
	global_load_lds_dwordx4 v128, s[64:65]
	s_waitcnt vmcnt(8)
	s_waitcnt lgkmcnt(0)
	s_barrier
	s_setprio 1
	s_waitcnt lgkmcnt(0)
	v_mfma_scale_f32_16x16x128_f8f6f4 v[48:51], v[134:141], v[64:71], v[48:51], v154, v154 op_sel_hi:[0,0,0]
	v_mfma_scale_f32_16x16x128_f8f6f4 v[52:55], v[156:163], v[64:71], v[52:55], v154, v154 op_sel_hi:[0,0,0]
	v_mfma_scale_f32_16x16x128_f8f6f4 v[206:209], v[134:141], v[72:79], v[32:35], v154, v154 op_sel_hi:[0,0,0]
	v_mfma_scale_f32_16x16x128_f8f6f4 v[210:213], v[156:163], v[72:79], v[36:39], v154, v154 op_sel_hi:[0,0,0]
	v_mfma_scale_f32_16x16x128_f8f6f4 v[214:217], v[134:141], v[80:87], v[16:19], v154, v154 op_sel_hi:[0,0,0]
	v_mfma_scale_f32_16x16x128_f8f6f4 v[218:221], v[156:163], v[80:87], v[20:23], v154, v154 op_sel_hi:[0,0,0]
	v_mfma_scale_f32_16x16x128_f8f6f4 v[226:229], v[134:141], v[88:95], v[4:7], v154, v154 op_sel_hi:[0,0,0]
	v_mfma_scale_f32_16x16x128_f8f6f4 v[230:233], v[156:163], v[88:95], v[8:11], v154, v154 op_sel_hi:[0,0,0]
	v_mfma_scale_f32_16x16x128_f8f6f4 v[56:59], v[164:171], v[64:71], v[56:59], v154, v154 op_sel_hi:[0,0,0]
	v_mfma_scale_f32_16x16x128_f8f6f4 v[60:63], v[178:185], v[64:71], v[60:63], v154, v154 op_sel_hi:[0,0,0]
	v_mfma_scale_f32_16x16x128_f8f6f4 v[234:237], v[164:171], v[72:79], v[40:43], v154, v154 op_sel_hi:[0,0,0]
	v_mfma_scale_f32_16x16x128_f8f6f4 v[238:241], v[178:185], v[72:79], v[44:47], v154, v154 op_sel_hi:[0,0,0]
	v_mfma_scale_f32_16x16x128_f8f6f4 v[242:245], v[164:171], v[80:87], v[24:27], v154, v154 op_sel_hi:[0,0,0]
	v_mfma_scale_f32_16x16x128_f8f6f4 v[246:249], v[178:185], v[80:87], v[28:31], v154, v154 op_sel_hi:[0,0,0]
	v_mfma_scale_f32_16x16x128_f8f6f4 v[250:253], v[164:171], v[88:95], v[12:15], v154, v154 op_sel_hi:[0,0,0]
	v_mfma_scale_f32_16x16x128_f8f6f4 v[130:133], v[178:185], v[88:95], v[0:3], v154, v154 op_sel_hi:[0,0,0]
	s_setprio 0
	s_barrier
; #define PG8_STAGE(bufoff, gbase, voff) do { _Pragma("unroll") for (int _i = 0; _i < 2; ++_i) { unsigned vo_ = (voff)[_i]; if constexpr (FP8) asm volatile("" : "+v"(vo_)); \
;         __builtin_amdgcn_global_load_lds((const unsigned*)((const char*)(gbase) + vo_), (PG8_LAS unsigned*)(lds + (bufoff) + ldsw + _i * 8192), 16, 0, 0); } } while (0)
; #define PG8_LDA(dst, b, h) do { _Pragma("unroll") for (int m = 0; m < 4; ++m) _Pragma("unroll") for (int k = 0; k < 2; ++k) dst[m][k] = *(const PG8_LAS bf16x8*)(lds + PG8_SA(b, h) + aoff + m * 2048 + k * 1024); } while (0)
; #define PG8_LDB(dst, b, h) do { _Pragma("unroll") for (int n = 0; n < 2; ++n) _Pragma("unroll") for (int k = 0; k < 2; ++k) dst[n][k] = *(const PG8_LAS bf16x8*)(lds + PG8_SB(b, h) + boff + n * 2048 + k * 1024); } while (0)
; #define PG8_WAIT_V(n) asm volatile("s_waitcnt vmcnt(" #n ")" ::: "memory")
; #define PG8_WAIT_L(n) asm volatile("s_waitcnt lgkmcnt(" #n ")" ::: "memory")
; #define PG8_BAR __builtin_amdgcn_s_barrier()
; #define PG8_SCHED __builtin_amdgcn_sched_barrier(0)
; template <class Epi, class Sched, bool ALIGN_EPI = false, bool SP2 = false, bool FP8 = false>
; __device__ __forceinline__ void gemm_phase(PG8_LAS unsigned char* lds, const Gemm g, const Sched& S, const Epi& E) {
;     ...
;             PG8_LDB(B0, 1, 0); PG8_LDB(B1, 1, 1); PG8_SCHED; PG8_LDA(At, 1, 0); PG8_STAGE(PG8_SA(0, 1), a2 + hstep, voffA);
;             PG8_WAIT_V(8); PG8_WAIT_L(0); PG8_BAR; PG8_MMA(0, 0, At, B0); PG8_MMA(0, 1, At, B1); PG8_BAR; PG8_SCHED;
;             PG8_LDA(At, 1, 1); PG8_STAGE(PG8_SB(1, 0), b3, voffB); PG8_STAGE(PG8_SB(1, 1), b3 + hstep, voffB); PG8_STAGE(PG8_SA(1, 0), a3, voffA);
;             PG8_WAIT_V(8); PG8_WAIT_L(0); PG8_BAR; PG8_MMA(1, 0, At, B0); PG8_MMA(1, 1, At, B1); PG8_BAR; PG8_SCHED;
	s_add_i32 s52, 0, 0x18000
	s_add_i32 s53, 0, 0x1c000
	s_nop 1
	v_add_u32_e32 v12, s52, v152
	v_add_u32_e32 v16, s53, v152
	ds_read_b128 v[0:3], v12
	ds_read_b128 v[4:7], v12 offset:1024
	ds_read_b128 v[8:11], v12 offset:2048
	ds_read_b128 v[12:15], v12 offset:3072
	ds_read_b128 v[134:137], v16
	ds_read_b128 v[138:141], v16 offset:1024
	ds_read_b128 v[156:159], v16 offset:2048
	ds_read_b128 v[160:163], v16 offset:3072
	s_add_u32 s0, s64, 0x18000
	v_mov_b32_e32 v64, v146
	s_mov_b32 m0, s70
	ds_read_b128 v[16:19], v153 offset:32768
	ds_read_b128 v[20:23], v153 offset:33792
	ds_read_b128 v[24:27], v153 offset:34816
	ds_read_b128 v[28:31], v153 offset:35840
	ds_read_b128 v[32:35], v153 offset:36864
	ds_read_b128 v[36:39], v153 offset:37888
	ds_read_b128 v[40:43], v153 offset:38912
	ds_read_b128 v[44:47], v153 offset:39936
	s_addc_u32 s1, s65, 0
	s_nop 0
	global_load_lds_dwordx4 v64, s[0:1]
	v_mov_b32_e32 v64, v148
	s_mov_b32 m0, s71
	s_nop 0
	global_load_lds_dwordx4 v64, s[0:1]
	s_waitcnt vmcnt(8)
	s_waitcnt lgkmcnt(0)
	s_barrier
	s_setprio 1
	s_waitcnt lgkmcnt(0)
	v_mfma_scale_f32_16x16x128_f8f6f4 v[112:115], v[0:7], v[16:23], v[112:115], v154, v154 op_sel_hi:[0,0,0]
	v_mfma_scale_f32_16x16x128_f8f6f4 v[116:119], v[8:15], v[16:23], v[116:119], v154, v154 op_sel_hi:[0,0,0]
	v_mfma_scale_f32_16x16x128_f8f6f4 v[96:99], v[0:7], v[24:31], v[96:99], v154, v154 op_sel_hi:[0,0,0]
	v_mfma_scale_f32_16x16x128_f8f6f4 v[100:103], v[8:15], v[24:31], v[100:103], v154, v154 op_sel_hi:[0,0,0]
	v_mfma_scale_f32_16x16x128_f8f6f4 v[80:83], v[0:7], v[32:39], v[142:145], v154, v154 op_sel_hi:[0,0,0]
	v_mfma_scale_f32_16x16x128_f8f6f4 v[84:87], v[8:15], v[32:39], v[172:175], v154, v154 op_sel_hi:[0,0,0]
	v_mfma_scale_f32_16x16x128_f8f6f4 v[64:67], v[0:7], v[40:47], v[194:197], v154, v154 op_sel_hi:[0,0,0]
	v_mfma_scale_f32_16x16x128_f8f6f4 v[68:71], v[8:15], v[40:47], v[222:225], v154, v154 op_sel_hi:[0,0,0]
	v_mfma_scale_f32_16x16x128_f8f6f4 v[120:123], v[134:141], v[16:23], v[120:123], v154, v154 op_sel_hi:[0,0,0]
	v_mfma_scale_f32_16x16x128_f8f6f4 v[124:127], v[156:163], v[16:23], v[124:127], v154, v154 op_sel_hi:[0,0,0]
	v_mfma_scale_f32_16x16x128_f8f6f4 v[104:107], v[134:141], v[24:31], v[104:107], v154, v154 op_sel_hi:[0,0,0]
	v_mfma_scale_f32_16x16x128_f8f6f4 v[108:111], v[156:163], v[24:31], v[108:111], v154, v154 op_sel_hi:[0,0,0]
	v_mfma_scale_f32_16x16x128_f8f6f4 v[88:91], v[134:141], v[32:39], v[186:189], v154, v154 op_sel_hi:[0,0,0]
	v_mfma_scale_f32_16x16x128_f8f6f4 v[92:95], v[156:163], v[32:39], v[190:193], v154, v154 op_sel_hi:[0,0,0]
	v_mfma_scale_f32_16x16x128_f8f6f4 v[72:75], v[134:141], v[40:47], v[198:201], v154, v154 op_sel_hi:[0,0,0]
	v_mfma_scale_f32_16x16x128_f8f6f4 v[76:79], v[156:163], v[40:47], v[202:205], v154, v154 op_sel_hi:[0,0,0]
	s_setprio 0
	s_barrier
	v_mov_b32_e32 v128, v147
	ds_read_b128 v[24:27], v153 offset:49152
	ds_read_b128 v[28:31], v153 offset:50176
	ds_read_b128 v[164:167], v153 offset:51200
	ds_read_b128 v[168:171], v153 offset:52224
	ds_read_b128 v[178:181], v153 offset:53248
	ds_read_b128 v[182:185], v153 offset:54272
	ds_read_b128 v[186:189], v153 offset:55296
	ds_read_b128 v[190:193], v153 offset:56320
	s_add_i32 s0, s52, s66
	v_lshl_add_u64 v[16:17], s[62:63], 0, v[128:129]
	v_lshl_add_u64 v[16:17], v[16:17], 0, s[40:41]
	s_mov_b32 m0, s0
	v_mov_b32_e32 v128, v149
	global_load_lds_dwordx4 v[16:17], off
	s_add_i32 m0, s0, 0x2000
	v_lshl_add_u64 v[16:17], s[62:63], 0, v[128:129]
	v_lshl_add_u64 v[16:17], v[16:17], 0, s[40:41]
	s_add_u32 s0, s62, 0x18080
	global_load_lds_dwordx4 v[16:17], off
	s_addc_u32 s1, s63, 0
	v_mov_b32_e32 v16, v147
	s_add_i32 s52, s53, s66
	s_mov_b32 m0, s52
	v_mov_b32_e32 v128, v146
	global_load_lds_dwordx4 v16, s[0:1]
	v_mov_b32_e32 v16, v149
	s_add_i32 m0, s52, 0x2000
	s_nop 0
	global_load_lds_dwordx4 v16, s[0:1]
	s_mov_b32 m0, s75
	v_lshl_add_u64 v[16:17], s[64:65], 0, v[128:129]
	v_lshl_add_u64 v[16:17], v[16:17], 0, s[40:41]
	v_mov_b32_e32 v128, v148
	global_load_lds_dwordx4 v[16:17], off
	s_mov_b32 m0, s77
	v_lshl_add_u64 v[16:17], s[64:65], 0, v[128:129]
	v_lshl_add_u64 v[16:17], v[16:17], 0, s[40:41]
	global_load_lds_dwordx4 v[16:17], off
	s_waitcnt vmcnt(8)
	s_waitcnt lgkmcnt(0)
	s_barrier
	s_setprio 1
	s_waitcnt lgkmcnt(0)
	v_mfma_scale_f32_16x16x128_f8f6f4 v[48:51], v[0:7], v[24:31], v[48:51], v154, v154 op_sel_hi:[0,0,0]
	v_mfma_scale_f32_16x16x128_f8f6f4 v[52:55], v[8:15], v[24:31], v[52:55], v154, v154 op_sel_hi:[0,0,0]
	v_mfma_scale_f32_16x16x128_f8f6f4 v[32:35], v[0:7], v[164:171], v[206:209], v154, v154 op_sel_hi:[0,0,0]
	v_mfma_scale_f32_16x16x128_f8f6f4 v[36:39], v[8:15], v[164:171], v[210:213], v154, v154 op_sel_hi:[0,0,0]
	v_mfma_scale_f32_16x16x128_f8f6f4 v[16:19], v[0:7], v[178:185], v[214:217], v154, v154 op_sel_hi:[0,0,0]
	v_mfma_scale_f32_16x16x128_f8f6f4 v[20:23], v[8:15], v[178:185], v[218:221], v154, v154 op_sel_hi:[0,0,0]
	v_mfma_scale_f32_16x16x128_f8f6f4 v[4:7], v[0:7], v[186:193], v[226:229], v154, v154 op_sel_hi:[0,0,0]
	v_mfma_scale_f32_16x16x128_f8f6f4 v[8:11], v[8:15], v[186:193], v[230:233], v154, v154 op_sel_hi:[0,0,0]
	v_mfma_scale_f32_16x16x128_f8f6f4 v[56:59], v[134:141], v[24:31], v[56:59], v154, v154 op_sel_hi:[0,0,0]
	v_mfma_scale_f32_16x16x128_f8f6f4 v[60:63], v[156:163], v[24:31], v[60:63], v154, v154 op_sel_hi:[0,0,0]
	v_mfma_scale_f32_16x16x128_f8f6f4 v[40:43], v[134:141], v[164:171], v[234:237], v154, v154 op_sel_hi:[0,0,0]
	v_mfma_scale_f32_16x16x128_f8f6f4 v[44:47], v[156:163], v[164:171], v[238:241], v154, v154 op_sel_hi:[0,0,0]
	v_mfma_scale_f32_16x16x128_f8f6f4 v[24:27], v[134:141], v[178:185], v[242:245], v154, v154 op_sel_hi:[0,0,0]
	v_mfma_scale_f32_16x16x128_f8f6f4 v[28:31], v[156:163], v[178:185], v[246:249], v154, v154 op_sel_hi:[0,0,0]
	v_mfma_scale_f32_16x16x128_f8f6f4 v[12:15], v[134:141], v[186:193], v[250:253], v154, v154 op_sel_hi:[0,0,0]
	v_mfma_scale_f32_16x16x128_f8f6f4 v[0:3], v[156:163], v[186:193], v[130:133], v154, v154 op_sel_hi:[0,0,0]
	s_setprio 0
	s_barrier
	s_add_i32 s91, s91, 2
	s_add_u32 s10, s10, 0x100
	s_addc_u32 s11, s11, 0
	s_add_u32 s89, s89, 0x100
	s_addc_u32 s90, s90, 0
	s_cmp_gt_u32 s91, 3
	s_cbranch_scc1 .LBB0_308

; #define PG8_STAGE(bufoff, gbase, voff) do { _Pragma("unroll") for (int _i = 0; _i < 2; ++_i) { unsigned vo_ = (voff)[_i]; if constexpr (FP8) asm volatile("" : "+v"(vo_)); \
;         __builtin_amdgcn_global_load_lds((const unsigned*)((const char*)(gbase) + vo_), (PG8_LAS unsigned*)(lds + (bufoff) + ldsw + _i * 8192), 16, 0, 0); } } while (0)
; #define PG8_LDA(dst, b, h) do { _Pragma("unroll") for (int m = 0; m < 4; ++m) _Pragma("unroll") for (int k = 0; k < 2; ++k) dst[m][k] = *(const PG8_LAS bf16x8*)(lds + PG8_SA(b, h) + aoff + m * 2048 + k * 1024); } while (0)
; #define PG8_LDB(dst, b, h) do { _Pragma("unroll") for (int n = 0; n < 2; ++n) _Pragma("unroll") for (int k = 0; k < 2; ++k) dst[n][k] = *(const PG8_LAS bf16x8*)(lds + PG8_SB(b, h) + boff + n * 2048 + k * 1024); } while (0)
; #define PG8_WAIT_V(n) asm volatile("s_waitcnt vmcnt(" #n ")" ::: "memory")
; #define PG8_WAIT_L(n) asm volatile("s_waitcnt lgkmcnt(" #n ")" ::: "memory")
; #define PG8_BAR __builtin_amdgcn_s_barrier()
; #define PG8_SCHED __builtin_amdgcn_sched_barrier(0)
; template <class Epi, class Sched, bool ALIGN_EPI = false, bool SP2 = false, bool FP8 = false>
; __device__ __forceinline__ void gemm_phase(PG8_LAS unsigned char* lds, const Gemm g, const Sched& S, const Epi& E) {
;     ...
;             PG8_LDB(B0, 0, 0); PG8_LDB(B1, 0, 1); PG8_SCHED; PG8_LDA(At, 0, 0); PG8_STAGE(PG8_SA(1, 1), a1 + hstep, voffA);
;             PG8_WAIT_V(8); PG8_WAIT_L(0); PG8_BAR; PG8_MMA(0, 0, At, B0); PG8_MMA(0, 1, At, B1); PG8_BAR; PG8_SCHED;
;             PG8_LDA(At, 0, 1); PG8_STAGE(PG8_SB(0, 0), b2, voffB); PG8_STAGE(PG8_SB(0, 1), b2 + hstep, voffB); PG8_STAGE(PG8_SA(0, 0), a2, voffA);
;             PG8_WAIT_V(8); PG8_WAIT_L(0); PG8_BAR; PG8_MMA(1, 0, At, B0); PG8_MMA(1, 1, At, B1); PG8_BAR; PG8_SCHED;
.Lmy_nobar_P4:
.LBB0_342:
	v_add_u32_e32 v140, s69, v201
	v_add_u32_e32 v156, s70, v201
	ds_read_b128 v[128:131], v140
	ds_read_b128 v[132:135], v140 offset:1024
	ds_read_b128 v[136:139], v140 offset:2048
	ds_read_b128 v[140:143], v140 offset:3072
	ds_read_b128 v[144:147], v156
	ds_read_b128 v[148:151], v156 offset:1024
	ds_read_b128 v[152:155], v156 offset:2048
	ds_read_b128 v[156:159], v156 offset:3072
	s_add_u32 s0, s10, 0xfffe0080
	s_addc_u32 s1, s11, -1
	s_cmp_eq_u32 s74, 4
	s_cselect_b32 s55, s9, s1
	s_cselect_b32 s54, s45, s0
	s_cselect_b32 s57, s43, s73
	s_cselect_b32 s56, s51, s72
	v_mov_b32_e32 v178, v197
	ds_read_b128 v[160:163], v202
	ds_read_b128 v[164:167], v202 offset:1024
	ds_read_b128 v[168:171], v202 offset:2048
	ds_read_b128 v[172:175], v202 offset:3072
	ds_read_b128 v[184:187], v202 offset:4096
	ds_read_b128 v[188:191], v202 offset:5120
	ds_read_b128 v[206:209], v202 offset:6144
	ds_read_b128 v[210:213], v202 offset:7168
	s_add_i32 m0, s53, 0xc000
	s_nop 0
	global_load_lds_dwordx4 v178, s[10:11]
	v_mov_b32_e32 v178, v199
	s_add_i32 m0, s53, 0xe000
	s_nop 0
	global_load_lds_dwordx4 v178, s[10:11]
	s_waitcnt vmcnt(8)
	s_waitcnt lgkmcnt(0)
	s_barrier
	s_setprio 1
	s_waitcnt lgkmcnt(0)
	v_mfma_scale_f32_16x16x128_f8f6f4 v[116:119], v[128:135], v[160:167], v[116:119], v203, v203 op_sel_hi:[0,0,0]
	v_mfma_scale_f32_16x16x128_f8f6f4 v[112:115], v[136:143], v[160:167], v[112:115], v203, v203 op_sel_hi:[0,0,0]
	v_mfma_scale_f32_16x16x128_f8f6f4 v[108:111], v[128:135], v[168:175], v[108:111], v203, v203 op_sel_hi:[0,0,0]
	v_mfma_scale_f32_16x16x128_f8f6f4 v[100:103], v[136:143], v[168:175], v[100:103], v203, v203 op_sel_hi:[0,0,0]
	v_mfma_scale_f32_16x16x128_f8f6f4 v[192:195], v[128:135], v[184:191], v[92:95], v203, v203 op_sel_hi:[0,0,0]
	v_mfma_scale_f32_16x16x128_f8f6f4 v[214:217], v[136:143], v[184:191], v[84:87], v203, v203 op_sel_hi:[0,0,0]
	v_mfma_scale_f32_16x16x128_f8f6f4 v[218:221], v[128:135], v[206:213], v[76:79], v203, v203 op_sel_hi:[0,0,0]
	v_mfma_scale_f32_16x16x128_f8f6f4 v[222:225], v[136:143], v[206:213], v[68:71], v203, v203 op_sel_hi:[0,0,0]
	v_mfma_scale_f32_16x16x128_f8f6f4 v[124:127], v[144:151], v[160:167], v[124:127], v203, v203 op_sel_hi:[0,0,0]
	v_mfma_scale_f32_16x16x128_f8f6f4 v[120:123], v[152:159], v[160:167], v[120:123], v203, v203 op_sel_hi:[0,0,0]
	v_mfma_scale_f32_16x16x128_f8f6f4 v[104:107], v[144:151], v[168:175], v[104:107], v203, v203 op_sel_hi:[0,0,0]
	v_mfma_scale_f32_16x16x128_f8f6f4 v[96:99], v[152:159], v[168:175], v[96:99], v203, v203 op_sel_hi:[0,0,0]
	v_mfma_scale_f32_16x16x128_f8f6f4 v[160:163], v[144:151], v[184:191], v[88:91], v203, v203 op_sel_hi:[0,0,0]
	v_mfma_scale_f32_16x16x128_f8f6f4 v[164:167], v[152:159], v[184:191], v[80:83], v203, v203 op_sel_hi:[0,0,0]
	v_mfma_scale_f32_16x16x128_f8f6f4 v[168:171], v[144:151], v[206:213], v[72:75], v203, v203 op_sel_hi:[0,0,0]
	v_mfma_scale_f32_16x16x128_f8f6f4 v[172:175], v[152:159], v[206:213], v[64:67], v203, v203 op_sel_hi:[0,0,0]
	s_setprio 0
	s_barrier
	v_mov_b32_e32 v178, v198
	s_add_i32 s0, s69, s41
	s_nop 2
	ds_read_b128 v[64:67], v202 offset:16384
	ds_read_b128 v[68:71], v202 offset:17408
	ds_read_b128 v[72:75], v202 offset:18432
	ds_read_b128 v[76:79], v202 offset:19456
	ds_read_b128 v[80:83], v202 offset:20480
	ds_read_b128 v[84:87], v202 offset:21504
	ds_read_b128 v[88:91], v202 offset:22528
	ds_read_b128 v[92:95], v202 offset:23552
	s_mov_b32 m0, s0
	s_nop 0
	global_load_lds_dwordx4 v178, s[56:57]
	v_mov_b32_e32 v178, v200
	s_add_i32 m0, s0, 0x2000
	s_add_u32 s0, s56, 0x20000
	global_load_lds_dwordx4 v178, s[56:57]
	s_addc_u32 s1, s57, 0
	v_mov_b32_e32 v178, v198
	s_add_i32 s75, s70, s41
	s_mov_b32 m0, s75
	s_nop 0
	global_load_lds_dwordx4 v178, s[0:1]
	v_mov_b32_e32 v178, v200
	s_add_i32 m0, s75, 0x2000
	s_nop 0
	global_load_lds_dwordx4 v178, s[0:1]
	v_mov_b32_e32 v178, v197
	s_mov_b32 m0, s53
	s_nop 0
	global_load_lds_dwordx4 v178, s[54:55]
	v_mov_b32_e32 v178, v199
	s_mov_b32 m0, s58
	s_nop 0
	global_load_lds_dwordx4 v178, s[54:55]
	s_waitcnt vmcnt(8)
	s_waitcnt lgkmcnt(0)
	s_barrier
	s_setprio 1
	s_waitcnt lgkmcnt(0)
	v_mfma_scale_f32_16x16x128_f8f6f4 v[52:55], v[128:135], v[64:71], v[52:55], v203, v203 op_sel_hi:[0,0,0]
	v_mfma_scale_f32_16x16x128_f8f6f4 v[48:51], v[136:143], v[64:71], v[48:51], v203, v203 op_sel_hi:[0,0,0]
	v_mfma_scale_f32_16x16x128_f8f6f4 v[44:47], v[128:135], v[72:79], v[44:47], v203, v203 op_sel_hi:[0,0,0]
	v_mfma_scale_f32_16x16x128_f8f6f4 v[184:187], v[136:143], v[72:79], v[36:39], v203, v203 op_sel_hi:[0,0,0]
	v_mfma_scale_f32_16x16x128_f8f6f4 v[188:191], v[128:135], v[80:87], v[28:31], v203, v203 op_sel_hi:[0,0,0]
	v_mfma_scale_f32_16x16x128_f8f6f4 v[206:209], v[136:143], v[80:87], v[20:23], v203, v203 op_sel_hi:[0,0,0]
	v_mfma_scale_f32_16x16x128_f8f6f4 v[210:213], v[128:135], v[88:95], v[12:15], v203, v203 op_sel_hi:[0,0,0]
	v_mfma_scale_f32_16x16x128_f8f6f4 v[226:229], v[136:143], v[88:95], v[4:7], v203, v203 op_sel_hi:[0,0,0]
	v_mfma_scale_f32_16x16x128_f8f6f4 v[40:43], v[144:151], v[72:79], v[40:43], v203, v203 op_sel_hi:[0,0,0]
	v_mfma_scale_f32_16x16x128_f8f6f4 v[230:233], v[144:151], v[64:71], v[60:63], v203, v203 op_sel_hi:[0,0,0]
	v_mfma_scale_f32_16x16x128_f8f6f4 v[234:237], v[152:159], v[64:71], v[56:59], v203, v203 op_sel_hi:[0,0,0]
	v_mfma_scale_f32_16x16x128_f8f6f4 v[238:241], v[152:159], v[72:79], v[32:35], v203, v203 op_sel_hi:[0,0,0]
	v_mfma_scale_f32_16x16x128_f8f6f4 v[242:245], v[144:151], v[80:87], v[24:27], v203, v203 op_sel_hi:[0,0,0]
	v_mfma_scale_f32_16x16x128_f8f6f4 v[246:249], v[152:159], v[80:87], v[16:19], v203, v203 op_sel_hi:[0,0,0]
	v_mfma_scale_f32_16x16x128_f8f6f4 v[250:253], v[144:151], v[88:95], v[8:11], v203, v203 op_sel_hi:[0,0,0]
	v_mfma_scale_f32_16x16x128_f8f6f4 v[180:183], v[152:159], v[88:95], v[0:3], v203, v203 op_sel_hi:[0,0,0]
	s_setprio 0
	s_barrier
; #define PG8_STAGE(bufoff, gbase, voff) do { _Pragma("unroll") for (int _i = 0; _i < 2; ++_i) { unsigned vo_ = (voff)[_i]; if constexpr (FP8) asm volatile("" : "+v"(vo_)); \
;         __builtin_amdgcn_global_load_lds((const unsigned*)((const char*)(gbase) + vo_), (PG8_LAS unsigned*)(lds + (bufoff) + ldsw + _i * 8192), 16, 0, 0); } } while (0)
; #define PG8_LDA(dst, b, h) do { _Pragma("unroll") for (int m = 0; m < 4; ++m) _Pragma("unroll") for (int k = 0; k < 2; ++k) dst[m][k] = *(const PG8_LAS bf16x8*)(lds + PG8_SA(b, h) + aoff + m * 2048 + k * 1024); } while (0)
; #define PG8_LDB(dst, b, h) do { _Pragma("unroll") for (int n = 0; n < 2; ++n) _Pragma("unroll") for (int k = 0; k < 2; ++k) dst[n][k] = *(const PG8_LAS bf16x8*)(lds + PG8_SB(b, h) + boff + n * 2048 + k * 1024); } while (0)
; #define PG8_WAIT_V(n) asm volatile("s_waitcnt vmcnt(" #n ")" ::: "memory")
; #define PG8_WAIT_L(n) asm volatile("s_waitcnt lgkmcnt(" #n ")" ::: "memory")
; #define PG8_BAR __builtin_amdgcn_s_barrier()
; #define PG8_SCHED __builtin_amdgcn_sched_barrier(0)
; template <class Epi, class Sched, bool ALIGN_EPI = false, bool SP2 = false, bool FP8 = false>
; __device__ __forceinline__ void gemm_phase(PG8_LAS unsigned char* lds, const Gemm g, const Sched& S, const Epi& E) {
;     ...
;             PG8_LDB(B0, 1, 0); PG8_LDB(B1, 1, 1); PG8_SCHED; PG8_LDA(At, 1, 0); PG8_STAGE(PG8_SA(0, 1), a2 + hstep, voffA);
;             PG8_WAIT_V(8); PG8_WAIT_L(0); PG8_BAR; PG8_MMA(0, 0, At, B0); PG8_MMA(0, 1, At, B1); PG8_BAR; PG8_SCHED;
;             PG8_LDA(At, 1, 1); PG8_STAGE(PG8_SB(1, 0), b3, voffB); PG8_STAGE(PG8_SB(1, 1), b3 + hstep, voffB); PG8_STAGE(PG8_SA(1, 0), a3, voffA);
;             PG8_WAIT_V(8); PG8_WAIT_L(0); PG8_BAR; PG8_MMA(1, 0, At, B0); PG8_MMA(1, 1, At, B1); PG8_BAR; PG8_SCHED;
	s_add_i32 s75, 0, 0x18000
	s_nop 2
	v_add_u32_e32 v8, s75, v201
	s_add_i32 s77, 0, 0x1c000
	ds_read_b128 v[0:3], v8
	ds_read_b128 v[4:7], v8 offset:1024
	ds_read_b128 v[56:59], v8 offset:2048
	ds_read_b128 v[60:63], v8 offset:3072
	v_add_u32_e32 v8, s77, v201
	ds_read_b128 v[128:131], v8
	ds_read_b128 v[132:135], v8 offset:1024
	ds_read_b128 v[136:139], v8 offset:2048
	ds_read_b128 v[140:143], v8 offset:3072
	s_add_u32 s0, s54, 0x20000
	v_mov_b32_e32 v64, v197
	s_mov_b32 m0, s59
	ds_read_b128 v[8:11], v202 offset:32768
	ds_read_b128 v[12:15], v202 offset:33792
	ds_read_b128 v[16:19], v202 offset:34816
	ds_read_b128 v[20:23], v202 offset:35840
	ds_read_b128 v[24:27], v202 offset:36864
	ds_read_b128 v[28:31], v202 offset:37888
	ds_read_b128 v[32:35], v202 offset:38912
	ds_read_b128 v[36:39], v202 offset:39936
	s_addc_u32 s1, s55, 0
	s_nop 0
	global_load_lds_dwordx4 v64, s[0:1]
	v_mov_b32_e32 v64, v199
	s_mov_b32 m0, s60
	s_nop 0
	global_load_lds_dwordx4 v64, s[0:1]
	s_waitcnt vmcnt(8)
	s_waitcnt lgkmcnt(0)
	s_barrier
	s_setprio 1
	s_waitcnt lgkmcnt(0)
	v_mfma_scale_f32_16x16x128_f8f6f4 v[116:119], v[0:7], v[8:15], v[116:119], v203, v203 op_sel_hi:[0,0,0]
	v_mfma_scale_f32_16x16x128_f8f6f4 v[112:115], v[56:63], v[8:15], v[112:115], v203, v203 op_sel_hi:[0,0,0]
	v_mfma_scale_f32_16x16x128_f8f6f4 v[108:111], v[0:7], v[16:23], v[108:111], v203, v203 op_sel_hi:[0,0,0]
	v_mfma_scale_f32_16x16x128_f8f6f4 v[100:103], v[56:63], v[16:23], v[100:103], v203, v203 op_sel_hi:[0,0,0]
	v_mfma_scale_f32_16x16x128_f8f6f4 v[92:95], v[0:7], v[24:31], v[192:195], v203, v203 op_sel_hi:[0,0,0]
	v_mfma_scale_f32_16x16x128_f8f6f4 v[84:87], v[56:63], v[24:31], v[214:217], v203, v203 op_sel_hi:[0,0,0]
	v_mfma_scale_f32_16x16x128_f8f6f4 v[76:79], v[0:7], v[32:39], v[218:221], v203, v203 op_sel_hi:[0,0,0]
	v_mfma_scale_f32_16x16x128_f8f6f4 v[68:71], v[56:63], v[32:39], v[222:225], v203, v203 op_sel_hi:[0,0,0]
	v_mfma_scale_f32_16x16x128_f8f6f4 v[124:127], v[128:135], v[8:15], v[124:127], v203, v203 op_sel_hi:[0,0,0]
	v_mfma_scale_f32_16x16x128_f8f6f4 v[120:123], v[136:143], v[8:15], v[120:123], v203, v203 op_sel_hi:[0,0,0]
	v_mfma_scale_f32_16x16x128_f8f6f4 v[104:107], v[128:135], v[16:23], v[104:107], v203, v203 op_sel_hi:[0,0,0]
	v_mfma_scale_f32_16x16x128_f8f6f4 v[96:99], v[136:143], v[16:23], v[96:99], v203, v203 op_sel_hi:[0,0,0]
	v_mfma_scale_f32_16x16x128_f8f6f4 v[88:91], v[128:135], v[24:31], v[160:163], v203, v203 op_sel_hi:[0,0,0]
	v_mfma_scale_f32_16x16x128_f8f6f4 v[80:83], v[136:143], v[24:31], v[164:167], v203, v203 op_sel_hi:[0,0,0]
	v_mfma_scale_f32_16x16x128_f8f6f4 v[72:75], v[128:135], v[32:39], v[168:171], v203, v203 op_sel_hi:[0,0,0]
	v_mfma_scale_f32_16x16x128_f8f6f4 v[64:67], v[136:143], v[32:39], v[172:175], v203, v203 op_sel_hi:[0,0,0]
	s_setprio 0
	s_barrier
	v_mov_b32_e32 v178, v198
	ds_read_b128 v[144:147], v202 offset:49152
	ds_read_b128 v[148:151], v202 offset:50176
	ds_read_b128 v[152:155], v202 offset:51200
	ds_read_b128 v[156:159], v202 offset:52224
	ds_read_b128 v[160:163], v202 offset:53248
	ds_read_b128 v[164:167], v202 offset:54272
	ds_read_b128 v[168:171], v202 offset:55296
	ds_read_b128 v[172:175], v202 offset:56320
	s_add_i32 s0, s75, s41
	v_lshl_add_u64 v[8:9], s[56:57], 0, v[178:179]
	v_lshl_add_u64 v[8:9], v[8:9], 0, s[14:15]
	s_mov_b32 m0, s0
	v_mov_b32_e32 v178, v200
	global_load_lds_dwordx4 v[8:9], off
	s_add_i32 m0, s0, 0x2000
	v_lshl_add_u64 v[8:9], s[56:57], 0, v[178:179]
	v_lshl_add_u64 v[8:9], v[8:9], 0, s[14:15]
	s_add_u32 s0, s56, 0x20080
	global_load_lds_dwordx4 v[8:9], off
	s_addc_u32 s1, s57, 0
	v_mov_b32_e32 v8, v198
	s_add_i32 s56, s77, s41
	s_mov_b32 m0, s56
	v_mov_b32_e32 v178, v197
	global_load_lds_dwordx4 v8, s[0:1]
	v_mov_b32_e32 v8, v200
	s_add_i32 m0, s56, 0x2000
	s_nop 0
	global_load_lds_dwordx4 v8, s[0:1]
	s_mov_b32 m0, s66
	v_lshl_add_u64 v[8:9], s[54:55], 0, v[178:179]
	v_lshl_add_u64 v[8:9], v[8:9], 0, s[14:15]
	v_mov_b32_e32 v178, v199
	global_load_lds_dwordx4 v[8:9], off
	s_mov_b32 m0, s67
	v_lshl_add_u64 v[8:9], s[54:55], 0, v[178:179]
	v_lshl_add_u64 v[8:9], v[8:9], 0, s[14:15]
	global_load_lds_dwordx4 v[8:9], off
	s_waitcnt vmcnt(8)
	s_waitcnt lgkmcnt(0)
	s_barrier
	s_setprio 1
	s_waitcnt lgkmcnt(0)
	v_mfma_scale_f32_16x16x128_f8f6f4 v[52:55], v[0:7], v[144:151], v[52:55], v203, v203 op_sel_hi:[0,0,0]
	v_mfma_scale_f32_16x16x128_f8f6f4 v[48:51], v[56:63], v[144:151], v[48:51], v203, v203 op_sel_hi:[0,0,0]
	v_mfma_scale_f32_16x16x128_f8f6f4 v[44:47], v[0:7], v[152:159], v[44:47], v203, v203 op_sel_hi:[0,0,0]
	v_mfma_scale_f32_16x16x128_f8f6f4 v[36:39], v[56:63], v[152:159], v[184:187], v203, v203 op_sel_hi:[0,0,0]
	v_mfma_scale_f32_16x16x128_f8f6f4 v[28:31], v[0:7], v[160:167], v[188:191], v203, v203 op_sel_hi:[0,0,0]
	v_mfma_scale_f32_16x16x128_f8f6f4 v[20:23], v[56:63], v[160:167], v[206:209], v203, v203 op_sel_hi:[0,0,0]
	v_mfma_scale_f32_16x16x128_f8f6f4 v[12:15], v[0:7], v[168:175], v[210:213], v203, v203 op_sel_hi:[0,0,0]
	v_mfma_scale_f32_16x16x128_f8f6f4 v[4:7], v[56:63], v[168:175], v[226:229], v203, v203 op_sel_hi:[0,0,0]
	v_mfma_scale_f32_16x16x128_f8f6f4 v[60:63], v[128:135], v[144:151], v[230:233], v203, v203 op_sel_hi:[0,0,0]
	v_mfma_scale_f32_16x16x128_f8f6f4 v[56:59], v[136:143], v[144:151], v[234:237], v203, v203 op_sel_hi:[0,0,0]
	v_mfma_scale_f32_16x16x128_f8f6f4 v[40:43], v[128:135], v[152:159], v[40:43], v203, v203 op_sel_hi:[0,0,0]
	v_mfma_scale_f32_16x16x128_f8f6f4 v[32:35], v[136:143], v[152:159], v[238:241], v203, v203 op_sel_hi:[0,0,0]
	v_mfma_scale_f32_16x16x128_f8f6f4 v[24:27], v[128:135], v[160:167], v[242:245], v203, v203 op_sel_hi:[0,0,0]
	v_mfma_scale_f32_16x16x128_f8f6f4 v[16:19], v[136:143], v[160:167], v[246:249], v203, v203 op_sel_hi:[0,0,0]
	v_mfma_scale_f32_16x16x128_f8f6f4 v[8:11], v[128:135], v[168:175], v[250:253], v203, v203 op_sel_hi:[0,0,0]
	v_mfma_scale_f32_16x16x128_f8f6f4 v[0:3], v[136:143], v[168:175], v[180:183], v203, v203 op_sel_hi:[0,0,0]
	s_setprio 0
	s_barrier
	s_add_i32 s74, s74, 2
	s_add_u32 s10, s10, 0x100
	s_addc_u32 s11, s11, 0
	s_add_u32 s72, s72, 0x100
	s_addc_u32 s73, s73, 0
	s_cmp_gt_u32 s74, 5
	s_cbranch_scc0 .LBB0_342
	s_and_b64 vcc, exec, s[38:39]
	s_cbranch_vccz .LBB0_345

; #define PG8_STAGE(bufoff, gbase, voff) do { _Pragma("unroll") for (int _i = 0; _i < 2; ++_i) { unsigned vo_ = (voff)[_i]; if constexpr (FP8) asm volatile("" : "+v"(vo_)); \
;         __builtin_amdgcn_global_load_lds((const unsigned*)((const char*)(gbase) + vo_), (PG8_LAS unsigned*)(lds + (bufoff) + ldsw + _i * 8192), 16, 0, 0); } } while (0)
; #define PG8_LDA(dst, b, h) do { _Pragma("unroll") for (int m = 0; m < 4; ++m) _Pragma("unroll") for (int k = 0; k < 2; ++k) dst[m][k] = *(const PG8_LAS bf16x8*)(lds + PG8_SA(b, h) + aoff + m * 2048 + k * 1024); } while (0)
; #define PG8_LDB(dst, b, h) do { _Pragma("unroll") for (int n = 0; n < 2; ++n) _Pragma("unroll") for (int k = 0; k < 2; ++k) dst[n][k] = *(const PG8_LAS bf16x8*)(lds + PG8_SB(b, h) + boff + n * 2048 + k * 1024); } while (0)
; #define PG8_WAIT_V(n) asm volatile("s_waitcnt vmcnt(" #n ")" ::: "memory")
; #define PG8_WAIT_L(n) asm volatile("s_waitcnt lgkmcnt(" #n ")" ::: "memory")
; #define PG8_BAR __builtin_amdgcn_s_barrier()
; #define PG8_SCHED __builtin_amdgcn_sched_barrier(0)
; template <class Epi, class Sched, bool ALIGN_EPI = false, bool SP2 = false, bool FP8 = false>
; __device__ __forceinline__ void gemm_phase(PG8_LAS unsigned char* lds, const Gemm g, const Sched& S, const Epi& E) {
;     ...
;             PG8_LDB(B0, 0, 0); PG8_LDB(B1, 0, 1); PG8_SCHED; PG8_LDA(At, 0, 0); PG8_STAGE(PG8_SA(1, 1), a1 + hstep, voffA);
;             PG8_WAIT_V(8); PG8_WAIT_L(0); PG8_BAR; PG8_MMA(0, 0, At, B0); PG8_MMA(0, 1, At, B1); PG8_BAR; PG8_SCHED;
;             PG8_LDA(At, 0, 1); PG8_STAGE(PG8_SB(0, 0), b2, voffB); PG8_STAGE(PG8_SB(0, 1), b2 + hstep, voffB); PG8_STAGE(PG8_SA(0, 0), a2, voffA);
.Lmy_nobar_P5:
.LBB0_391:
	ds_read_b128 v[146:149], v153
	ds_read_b128 v[158:161], v153 offset:1024
	ds_read_b128 v[162:165], v153 offset:2048
	ds_read_b128 v[166:169], v153 offset:3072
	ds_read_b128 v[170:173], v154
	ds_read_b128 v[174:177], v154 offset:1024
	ds_read_b128 v[178:181], v154 offset:2048
	ds_read_b128 v[182:185], v154 offset:3072
	s_add_u32 s0, s40, 0xfffc0080
	s_addc_u32 s1, s41, -1
	s_cmp_eq_u32 s61, 12
	s_cselect_b32 s45, s15, s1
	s_cselect_b32 s44, s57, s0
	s_cselect_b32 s43, s13, s60
	s_cselect_b32 s42, s58, s59
	v_lshl_add_u64 v[218:219], s[40:41], 0, v[138:139]
	s_add_i32 m0, s39, 0xc000
	ds_read_b128 v[186:189], v155
	ds_read_b128 v[190:193], v155 offset:1024
	ds_read_b128 v[194:197], v155 offset:2048
	ds_read_b128 v[198:201], v155 offset:3072
	ds_read_b128 v[202:205], v155 offset:4096
	ds_read_b128 v[206:209], v155 offset:5120
	ds_read_b128 v[210:213], v155 offset:6144
	ds_read_b128 v[214:217], v155 offset:7168
	global_load_lds_dwordx4 v[218:219], off
	v_lshl_add_u64 v[218:219], s[40:41], 0, v[140:141]
	s_add_i32 m0, s39, 0xe000
	s_nop 0
	global_load_lds_dwordx4 v[218:219], off
	s_waitcnt vmcnt(8)
	s_waitcnt lgkmcnt(0)
	s_barrier
	s_setprio 1
	s_waitcnt lgkmcnt(0)
	v_mfma_f32_16x16x32_bf16 v[124:127], v[146:149], v[186:189], v[124:127]
	v_mfma_f32_16x16x32_bf16 v[120:123], v[162:165], v[186:189], v[120:123]
	v_mfma_f32_16x16x32_bf16 v[108:111], v[146:149], v[194:197], v[108:111]
	v_mfma_f32_16x16x32_bf16 v[104:107], v[162:165], v[194:197], v[104:107]
	v_mfma_f32_16x16x32_bf16 v[92:95], v[146:149], v[202:205], v[92:95]
	v_mfma_f32_16x16x32_bf16 v[88:91], v[162:165], v[202:205], v[88:91]
	v_mfma_f32_16x16x32_bf16 v[76:79], v[146:149], v[210:213], v[76:79]
	v_mfma_f32_16x16x32_bf16 v[72:75], v[162:165], v[210:213], v[72:75]
	v_mfma_f32_16x16x32_bf16 v[124:127], v[158:161], v[190:193], v[124:127]
	v_mfma_f32_16x16x32_bf16 v[120:123], v[166:169], v[190:193], v[120:123]
	v_mfma_f32_16x16x32_bf16 v[108:111], v[158:161], v[198:201], v[108:111]
	v_mfma_f32_16x16x32_bf16 v[104:107], v[166:169], v[198:201], v[104:107]
	v_mfma_f32_16x16x32_bf16 v[92:95], v[158:161], v[206:209], v[92:95]
	v_mfma_f32_16x16x32_bf16 v[88:91], v[166:169], v[206:209], v[88:91]
	v_mfma_f32_16x16x32_bf16 v[76:79], v[158:161], v[214:217], v[76:79]
	v_mfma_f32_16x16x32_bf16 v[72:75], v[166:169], v[214:217], v[72:75]
	v_mfma_f32_16x16x32_bf16 v[116:119], v[170:173], v[186:189], v[116:119]
	v_mfma_f32_16x16x32_bf16 v[112:115], v[178:181], v[186:189], v[112:115]
	v_mfma_f32_16x16x32_bf16 v[100:103], v[170:173], v[194:197], v[100:103]
	v_mfma_f32_16x16x32_bf16 v[96:99], v[178:181], v[194:197], v[96:99]
	v_mfma_f32_16x16x32_bf16 v[84:87], v[170:173], v[202:205], v[84:87]
	v_mfma_f32_16x16x32_bf16 v[80:83], v[178:181], v[202:205], v[80:83]
	v_mfma_f32_16x16x32_bf16 v[68:71], v[170:173], v[210:213], v[68:71]
	v_mfma_f32_16x16x32_bf16 v[64:67], v[178:181], v[210:213], v[64:67]
	v_mfma_f32_16x16x32_bf16 v[116:119], v[174:177], v[190:193], v[116:119]
	v_mfma_f32_16x16x32_bf16 v[112:115], v[182:185], v[190:193], v[112:115]
	v_mfma_f32_16x16x32_bf16 v[100:103], v[174:177], v[198:201], v[100:103]
	v_mfma_f32_16x16x32_bf16 v[96:99], v[182:185], v[198:201], v[96:99]
	v_mfma_f32_16x16x32_bf16 v[84:87], v[174:177], v[206:209], v[84:87]
	v_mfma_f32_16x16x32_bf16 v[80:83], v[182:185], v[206:209], v[80:83]
	v_mfma_f32_16x16x32_bf16 v[68:71], v[174:177], v[214:217], v[68:71]
	v_mfma_f32_16x16x32_bf16 v[64:67], v[182:185], v[214:217], v[64:67]
	s_setprio 0
	s_barrier
	s_add_i32 s0, s54, s46
	v_lshl_add_u64 v[218:219], s[42:43], 0, v[132:133]
	s_mov_b32 m0, s0
	ds_read_b128 v[186:189], v155 offset:16384
	ds_read_b128 v[190:193], v155 offset:17408
	ds_read_b128 v[194:197], v155 offset:18432
	ds_read_b128 v[198:201], v155 offset:19456
	ds_read_b128 v[202:205], v155 offset:20480
	ds_read_b128 v[206:209], v155 offset:21504
	ds_read_b128 v[210:213], v155 offset:22528
	ds_read_b128 v[214:217], v155 offset:23552
	global_load_lds_dwordx4 v[218:219], off
	s_add_i32 m0, s0, 0x2000
	s_add_u32 s0, s42, 0x40000
	v_lshl_add_u64 v[220:221], s[42:43], 0, v[128:129]
	s_addc_u32 s1, s43, 0
	s_add_i32 s62, s55, s46
	global_load_lds_dwordx4 v[220:221], off
	v_lshl_add_u64 v[222:223], s[0:1], 0, v[132:133]
	s_mov_b32 m0, s62
	v_lshl_add_u64 v[224:225], s[44:45], 0, v[130:131]
	global_load_lds_dwordx4 v[222:223], off
	v_lshl_add_u64 v[222:223], s[0:1], 0, v[128:129]
	s_add_i32 m0, s62, 0x2000
	s_nop 0
	global_load_lds_dwordx4 v[222:223], off
	v_lshl_add_u64 v[222:223], s[44:45], 0, v[134:135]
	s_mov_b32 m0, s39
	s_nop 0
	global_load_lds_dwordx4 v[222:223], off
	s_mov_b32 m0, s48
	s_nop 0
	global_load_lds_dwordx4 v[224:225], off
	s_waitcnt vmcnt(8)
	s_waitcnt lgkmcnt(0)
	s_barrier
; #define PG8_STAGE(bufoff, gbase, voff) do { _Pragma("unroll") for (int _i = 0; _i < 2; ++_i) { unsigned vo_ = (voff)[_i]; if constexpr (FP8) asm volatile("" : "+v"(vo_)); \
;         __builtin_amdgcn_global_load_lds((const unsigned*)((const char*)(gbase) + vo_), (PG8_LAS unsigned*)(lds + (bufoff) + ldsw + _i * 8192), 16, 0, 0); } } while (0)
; #define PG8_LDA(dst, b, h) do { _Pragma("unroll") for (int m = 0; m < 4; ++m) _Pragma("unroll") for (int k = 0; k < 2; ++k) dst[m][k] = *(const PG8_LAS bf16x8*)(lds + PG8_SA(b, h) + aoff + m * 2048 + k * 1024); } while (0)
; #define PG8_LDB(dst, b, h) do { _Pragma("unroll") for (int n = 0; n < 2; ++n) _Pragma("unroll") for (int k = 0; k < 2; ++k) dst[n][k] = *(const PG8_LAS bf16x8*)(lds + PG8_SB(b, h) + boff + n * 2048 + k * 1024); } while (0)
; #define PG8_WAIT_V(n) asm volatile("s_waitcnt vmcnt(" #n ")" ::: "memory")
; #define PG8_WAIT_L(n) asm volatile("s_waitcnt lgkmcnt(" #n ")" ::: "memory")
; #define PG8_BAR __builtin_amdgcn_s_barrier()
; #define PG8_SCHED __builtin_amdgcn_sched_barrier(0)
; template <class Epi, class Sched, bool ALIGN_EPI = false, bool SP2 = false, bool FP8 = false>
; __device__ __forceinline__ void gemm_phase(PG8_LAS unsigned char* lds, const Gemm g, const Sched& S, const Epi& E) {
;     ...
;             PG8_WAIT_V(8); PG8_WAIT_L(0); PG8_BAR; PG8_MMA(1, 0, At, B0); PG8_MMA(1, 1, At, B1); PG8_BAR; PG8_SCHED;
;             PG8_LDB(B0, 1, 0); PG8_LDB(B1, 1, 1); PG8_SCHED; PG8_LDA(At, 1, 0); PG8_STAGE(PG8_SA(0, 1), a2 + hstep, voffA);
;             PG8_WAIT_V(8); PG8_WAIT_L(0); PG8_BAR; PG8_MMA(0, 0, At, B0); PG8_MMA(0, 1, At, B1); PG8_BAR; PG8_SCHED;
	s_setprio 1
	s_waitcnt lgkmcnt(0)
	v_mfma_f32_16x16x32_bf16 v[60:63], v[146:149], v[186:189], v[60:63]
	v_mfma_f32_16x16x32_bf16 v[56:59], v[162:165], v[186:189], v[56:59]
	v_mfma_f32_16x16x32_bf16 v[44:47], v[146:149], v[194:197], v[44:47]
	v_mfma_f32_16x16x32_bf16 v[40:43], v[162:165], v[194:197], v[40:43]
	v_mfma_f32_16x16x32_bf16 v[28:31], v[146:149], v[202:205], v[28:31]
	v_mfma_f32_16x16x32_bf16 v[24:27], v[162:165], v[202:205], v[24:27]
	v_mfma_f32_16x16x32_bf16 v[12:15], v[146:149], v[210:213], v[12:15]
	v_mfma_f32_16x16x32_bf16 v[8:11], v[162:165], v[210:213], v[8:11]
	v_mfma_f32_16x16x32_bf16 v[60:63], v[158:161], v[190:193], v[60:63]
	v_mfma_f32_16x16x32_bf16 v[56:59], v[166:169], v[190:193], v[56:59]
	v_mfma_f32_16x16x32_bf16 v[44:47], v[158:161], v[198:201], v[44:47]
	v_mfma_f32_16x16x32_bf16 v[40:43], v[166:169], v[198:201], v[40:43]
	v_mfma_f32_16x16x32_bf16 v[28:31], v[158:161], v[206:209], v[28:31]
	v_mfma_f32_16x16x32_bf16 v[24:27], v[166:169], v[206:209], v[24:27]
	v_mfma_f32_16x16x32_bf16 v[12:15], v[158:161], v[214:217], v[12:15]
	v_mfma_f32_16x16x32_bf16 v[8:11], v[166:169], v[214:217], v[8:11]
	v_mfma_f32_16x16x32_bf16 v[52:55], v[170:173], v[186:189], v[52:55]
	v_mfma_f32_16x16x32_bf16 v[48:51], v[178:181], v[186:189], v[48:51]
	v_mfma_f32_16x16x32_bf16 v[36:39], v[170:173], v[194:197], v[36:39]
	v_mfma_f32_16x16x32_bf16 v[32:35], v[178:181], v[194:197], v[32:35]
	v_mfma_f32_16x16x32_bf16 v[20:23], v[170:173], v[202:205], v[20:23]
	v_mfma_f32_16x16x32_bf16 v[16:19], v[178:181], v[202:205], v[16:19]
	v_mfma_f32_16x16x32_bf16 v[4:7], v[170:173], v[210:213], v[4:7]
	v_mfma_f32_16x16x32_bf16 v[0:3], v[178:181], v[210:213], v[0:3]
	v_mfma_f32_16x16x32_bf16 v[52:55], v[174:177], v[190:193], v[52:55]
	v_mfma_f32_16x16x32_bf16 v[48:51], v[182:185], v[190:193], v[48:51]
	v_mfma_f32_16x16x32_bf16 v[36:39], v[174:177], v[198:201], v[36:39]
	v_mfma_f32_16x16x32_bf16 v[32:35], v[182:185], v[198:201], v[32:35]
	v_mfma_f32_16x16x32_bf16 v[20:23], v[174:177], v[206:209], v[20:23]
	v_mfma_f32_16x16x32_bf16 v[16:19], v[182:185], v[206:209], v[16:19]
	v_mfma_f32_16x16x32_bf16 v[4:7], v[174:177], v[214:217], v[4:7]
	v_mfma_f32_16x16x32_bf16 v[0:3], v[182:185], v[214:217], v[0:3]
	s_setprio 0
	s_barrier
	s_add_i32 s62, 0, 0x18000
	s_add_i32 s63, 0, 0x1c000
	v_add_u32_e32 v166, s62, v151
	v_add_u32_e32 v182, s63, v151
	ds_read_b128 v[146:149], v166
	ds_read_b128 v[158:161], v166 offset:1024
	ds_read_b128 v[162:165], v166 offset:2048
	ds_read_b128 v[166:169], v166 offset:3072
	ds_read_b128 v[170:173], v182
	ds_read_b128 v[174:177], v182 offset:1024
	ds_read_b128 v[178:181], v182 offset:2048
	ds_read_b128 v[182:185], v182 offset:3072
	s_add_u32 s0, s44, 0x40000
	s_addc_u32 s1, s45, 0
	s_mov_b32 m0, s49
	v_lshl_add_u64 v[226:227], s[0:1], 0, v[134:135]
	ds_read_b128 v[186:189], v155 offset:32768
	ds_read_b128 v[190:193], v155 offset:33792
	ds_read_b128 v[194:197], v155 offset:34816
	ds_read_b128 v[198:201], v155 offset:35840
	ds_read_b128 v[202:205], v155 offset:36864
	ds_read_b128 v[206:209], v155 offset:37888
	ds_read_b128 v[210:213], v155 offset:38912
	ds_read_b128 v[214:217], v155 offset:39936
	global_load_lds_dwordx4 v[226:227], off
	v_lshl_add_u64 v[226:227], s[0:1], 0, v[130:131]
	s_mov_b32 m0, s50
	s_nop 0
	global_load_lds_dwordx4 v[226:227], off
	s_waitcnt vmcnt(8)
	s_waitcnt lgkmcnt(0)
	s_barrier
	s_setprio 1
	s_waitcnt lgkmcnt(0)
	v_mfma_f32_16x16x32_bf16 v[124:127], v[146:149], v[186:189], v[124:127]
	v_mfma_f32_16x16x32_bf16 v[120:123], v[162:165], v[186:189], v[120:123]
	v_mfma_f32_16x16x32_bf16 v[108:111], v[146:149], v[194:197], v[108:111]
	v_mfma_f32_16x16x32_bf16 v[104:107], v[162:165], v[194:197], v[104:107]
	v_mfma_f32_16x16x32_bf16 v[92:95], v[146:149], v[202:205], v[92:95]
	v_mfma_f32_16x16x32_bf16 v[88:91], v[162:165], v[202:205], v[88:91]
	v_mfma_f32_16x16x32_bf16 v[76:79], v[146:149], v[210:213], v[76:79]
	v_mfma_f32_16x16x32_bf16 v[72:75], v[162:165], v[210:213], v[72:75]
	v_mfma_f32_16x16x32_bf16 v[124:127], v[158:161], v[190:193], v[124:127]
	v_mfma_f32_16x16x32_bf16 v[120:123], v[166:169], v[190:193], v[120:123]
	v_mfma_f32_16x16x32_bf16 v[108:111], v[158:161], v[198:201], v[108:111]
	v_mfma_f32_16x16x32_bf16 v[104:107], v[166:169], v[198:201], v[104:107]
	v_mfma_f32_16x16x32_bf16 v[92:95], v[158:161], v[206:209], v[92:95]
	v_mfma_f32_16x16x32_bf16 v[88:91], v[166:169], v[206:209], v[88:91]
	v_mfma_f32_16x16x32_bf16 v[76:79], v[158:161], v[214:217], v[76:79]
	v_mfma_f32_16x16x32_bf16 v[72:75], v[166:169], v[214:217], v[72:75]
	v_mfma_f32_16x16x32_bf16 v[116:119], v[170:173], v[186:189], v[116:119]
	v_mfma_f32_16x16x32_bf16 v[112:115], v[178:181], v[186:189], v[112:115]
	v_mfma_f32_16x16x32_bf16 v[100:103], v[170:173], v[194:197], v[100:103]
	v_mfma_f32_16x16x32_bf16 v[96:99], v[178:181], v[194:197], v[96:99]
	v_mfma_f32_16x16x32_bf16 v[84:87], v[170:173], v[202:205], v[84:87]
	v_mfma_f32_16x16x32_bf16 v[80:83], v[178:181], v[202:205], v[80:83]
	v_mfma_f32_16x16x32_bf16 v[68:71], v[170:173], v[210:213], v[68:71]
	v_mfma_f32_16x16x32_bf16 v[64:67], v[178:181], v[210:213], v[64:67]
	v_mfma_f32_16x16x32_bf16 v[116:119], v[174:177], v[190:193], v[116:119]
	v_mfma_f32_16x16x32_bf16 v[112:115], v[182:185], v[190:193], v[112:115]
	v_mfma_f32_16x16x32_bf16 v[100:103], v[174:177], v[198:201], v[100:103]
	v_mfma_f32_16x16x32_bf16 v[96:99], v[182:185], v[198:201], v[96:99]
	v_mfma_f32_16x16x32_bf16 v[84:87], v[174:177], v[206:209], v[84:87]
	v_mfma_f32_16x16x32_bf16 v[80:83], v[182:185], v[206:209], v[80:83]
	v_mfma_f32_16x16x32_bf16 v[68:71], v[174:177], v[214:217], v[68:71]
	v_mfma_f32_16x16x32_bf16 v[64:67], v[182:185], v[214:217], v[64:67]
	s_setprio 0
	s_barrier
; #define PG8_STAGE(bufoff, gbase, voff) do { _Pragma("unroll") for (int _i = 0; _i < 2; ++_i) { unsigned vo_ = (voff)[_i]; if constexpr (FP8) asm volatile("" : "+v"(vo_)); \
;         __builtin_amdgcn_global_load_lds((const unsigned*)((const char*)(gbase) + vo_), (PG8_LAS unsigned*)(lds + (bufoff) + ldsw + _i * 8192), 16, 0, 0); } } while (0)
; #define PG8_LDA(dst, b, h) do { _Pragma("unroll") for (int m = 0; m < 4; ++m) _Pragma("unroll") for (int k = 0; k < 2; ++k) dst[m][k] = *(const PG8_LAS bf16x8*)(lds + PG8_SA(b, h) + aoff + m * 2048 + k * 1024); } while (0)
; #define PG8_WAIT_V(n) asm volatile("s_waitcnt vmcnt(" #n ")" ::: "memory")
; #define PG8_WAIT_L(n) asm volatile("s_waitcnt lgkmcnt(" #n ")" ::: "memory")
; #define PG8_BAR __builtin_amdgcn_s_barrier()
; #define PG8_SCHED __builtin_amdgcn_sched_barrier(0)
; template <class Epi, class Sched, bool ALIGN_EPI = false, bool SP2 = false, bool FP8 = false>
; __device__ __forceinline__ void gemm_phase(PG8_LAS unsigned char* lds, const Gemm g, const Sched& S, const Epi& E) {
;     ...
;             PG8_LDA(At, 1, 1); PG8_STAGE(PG8_SB(1, 0), b3, voffB); PG8_STAGE(PG8_SB(1, 1), b3 + hstep, voffB); PG8_STAGE(PG8_SA(1, 0), a3, voffA);
;             PG8_WAIT_V(8); PG8_WAIT_L(0); PG8_BAR; PG8_MMA(1, 0, At, B0); PG8_MMA(1, 1, At, B1); PG8_BAR; PG8_SCHED;
	s_add_i32 s0, s62, s46
	v_lshl_add_u64 v[218:219], v[218:219], 0, s[8:9]
	s_mov_b32 m0, s0
	ds_read_b128 v[186:189], v155 offset:49152
	ds_read_b128 v[190:193], v155 offset:50176
	ds_read_b128 v[194:197], v155 offset:51200
	ds_read_b128 v[198:201], v155 offset:52224
	ds_read_b128 v[202:205], v155 offset:53248
	ds_read_b128 v[206:209], v155 offset:54272
	ds_read_b128 v[210:213], v155 offset:55296
	ds_read_b128 v[214:217], v155 offset:56320
	global_load_lds_dwordx4 v[218:219], off
	s_add_i32 m0, s0, 0x2000
	s_add_u32 s0, s42, 0x40080
	v_lshl_add_u64 v[218:219], v[220:221], 0, s[8:9]
	s_addc_u32 s1, s43, 0
	s_add_i32 s42, s63, s46
	global_load_lds_dwordx4 v[218:219], off
	v_lshl_add_u64 v[218:219], s[0:1], 0, v[132:133]
	s_mov_b32 m0, s42
	s_nop 0
	global_load_lds_dwordx4 v[218:219], off
	v_lshl_add_u64 v[218:219], s[0:1], 0, v[128:129]
	s_add_i32 m0, s42, 0x2000
	s_nop 0
	global_load_lds_dwordx4 v[218:219], off
	v_lshl_add_u64 v[218:219], v[222:223], 0, s[8:9]
	s_mov_b32 m0, s52
	s_nop 0
	global_load_lds_dwordx4 v[218:219], off
	v_lshl_add_u64 v[218:219], v[224:225], 0, s[8:9]
	s_mov_b32 m0, s53
	s_nop 0
	global_load_lds_dwordx4 v[218:219], off
	s_waitcnt vmcnt(8)
	s_waitcnt lgkmcnt(0)
	s_barrier
	s_setprio 1
	s_waitcnt lgkmcnt(0)
	v_mfma_f32_16x16x32_bf16 v[60:63], v[146:149], v[186:189], v[60:63]
	v_mfma_f32_16x16x32_bf16 v[56:59], v[162:165], v[186:189], v[56:59]
	v_mfma_f32_16x16x32_bf16 v[44:47], v[146:149], v[194:197], v[44:47]
	v_mfma_f32_16x16x32_bf16 v[40:43], v[162:165], v[194:197], v[40:43]
	v_mfma_f32_16x16x32_bf16 v[28:31], v[146:149], v[202:205], v[28:31]
	v_mfma_f32_16x16x32_bf16 v[24:27], v[162:165], v[202:205], v[24:27]
	v_mfma_f32_16x16x32_bf16 v[12:15], v[146:149], v[210:213], v[12:15]
	v_mfma_f32_16x16x32_bf16 v[8:11], v[162:165], v[210:213], v[8:11]
	v_mfma_f32_16x16x32_bf16 v[60:63], v[158:161], v[190:193], v[60:63]
	v_mfma_f32_16x16x32_bf16 v[56:59], v[166:169], v[190:193], v[56:59]
	v_mfma_f32_16x16x32_bf16 v[44:47], v[158:161], v[198:201], v[44:47]
	v_mfma_f32_16x16x32_bf16 v[40:43], v[166:169], v[198:201], v[40:43]
	v_mfma_f32_16x16x32_bf16 v[28:31], v[158:161], v[206:209], v[28:31]
	v_mfma_f32_16x16x32_bf16 v[24:27], v[166:169], v[206:209], v[24:27]
	v_mfma_f32_16x16x32_bf16 v[12:15], v[158:161], v[214:217], v[12:15]
	v_mfma_f32_16x16x32_bf16 v[8:11], v[166:169], v[214:217], v[8:11]
	v_mfma_f32_16x16x32_bf16 v[52:55], v[170:173], v[186:189], v[52:55]
	v_mfma_f32_16x16x32_bf16 v[48:51], v[178:181], v[186:189], v[48:51]
	v_mfma_f32_16x16x32_bf16 v[36:39], v[170:173], v[194:197], v[36:39]
	v_mfma_f32_16x16x32_bf16 v[32:35], v[178:181], v[194:197], v[32:35]
	v_mfma_f32_16x16x32_bf16 v[20:23], v[170:173], v[202:205], v[20:23]
	v_mfma_f32_16x16x32_bf16 v[16:19], v[178:181], v[202:205], v[16:19]
	v_mfma_f32_16x16x32_bf16 v[4:7], v[170:173], v[210:213], v[4:7]
	v_mfma_f32_16x16x32_bf16 v[0:3], v[178:181], v[210:213], v[0:3]
	v_mfma_f32_16x16x32_bf16 v[52:55], v[174:177], v[190:193], v[52:55]
	v_mfma_f32_16x16x32_bf16 v[48:51], v[182:185], v[190:193], v[48:51]
	v_mfma_f32_16x16x32_bf16 v[36:39], v[174:177], v[198:201], v[36:39]
	v_mfma_f32_16x16x32_bf16 v[32:35], v[182:185], v[198:201], v[32:35]
	v_mfma_f32_16x16x32_bf16 v[20:23], v[174:177], v[206:209], v[20:23]
	v_mfma_f32_16x16x32_bf16 v[16:19], v[182:185], v[206:209], v[16:19]
	v_mfma_f32_16x16x32_bf16 v[4:7], v[174:177], v[214:217], v[4:7]
	v_mfma_f32_16x16x32_bf16 v[0:3], v[182:185], v[214:217], v[0:3]
	s_setprio 0
	s_barrier
	s_add_i32 s61, s61, 2
	s_add_u32 s40, s40, 0x100
	s_addc_u32 s41, s41, 0
	s_add_u32 s59, s59, 0x100
	s_addc_u32 s60, s60, 0
	s_cmp_gt_u32 s61, 13
	s_cbranch_scc0 .LBB0_391
	s_and_b64 vcc, exec, s[10:11]
	s_cbranch_vccz .LBB0_394
	s_barrier

; #define PG8_STAGE(bufoff, gbase, voff) do { _Pragma("unroll") for (int _i = 0; _i < 2; ++_i) { unsigned vo_ = (voff)[_i]; if constexpr (FP8) asm volatile("" : "+v"(vo_)); \
;         __builtin_amdgcn_global_load_lds((const unsigned*)((const char*)(gbase) + vo_), (PG8_LAS unsigned*)(lds + (bufoff) + ldsw + _i * 8192), 16, 0, 0); } } while (0)
; #define PG8_LDA(dst, b, h) do { _Pragma("unroll") for (int m = 0; m < 4; ++m) _Pragma("unroll") for (int k = 0; k < 2; ++k) dst[m][k] = *(const PG8_LAS bf16x8*)(lds + PG8_SA(b, h) + aoff + m * 2048 + k * 1024); } while (0)
; #define PG8_LDB(dst, b, h) do { _Pragma("unroll") for (int n = 0; n < 2; ++n) _Pragma("unroll") for (int k = 0; k < 2; ++k) dst[n][k] = *(const PG8_LAS bf16x8*)(lds + PG8_SB(b, h) + boff + n * 2048 + k * 1024); } while (0)
; #define PG8_WAIT_V(n) asm volatile("s_waitcnt vmcnt(" #n ")" ::: "memory")
; #define PG8_WAIT_L(n) asm volatile("s_waitcnt lgkmcnt(" #n ")" ::: "memory")
; #define PG8_BAR __builtin_amdgcn_s_barrier()
; #define PG8_SCHED __builtin_amdgcn_sched_barrier(0)
; template <class Epi, class Sched, bool ALIGN_EPI = false, bool SP2 = false, bool FP8 = false>
; __device__ __forceinline__ void gemm_phase(PG8_LAS unsigned char* lds, const Gemm g, const Sched& S, const Epi& E) {
;     ...
;             PG8_LDB(B0, 0, 0); PG8_LDB(B1, 0, 1); PG8_SCHED; PG8_LDA(At, 0, 0); PG8_STAGE(PG8_SA(1, 1), a1 + hstep, voffA);
;             PG8_WAIT_V(8); PG8_WAIT_L(0); PG8_BAR; PG8_MMA(0, 0, At, B0); PG8_MMA(0, 1, At, B1); PG8_BAR; PG8_SCHED;
;             PG8_LDA(At, 0, 1); PG8_STAGE(PG8_SB(0, 0), b2, voffB); PG8_STAGE(PG8_SB(0, 1), b2 + hstep, voffB); PG8_STAGE(PG8_SA(0, 0), a2, voffA);
.Lmy_nobar_P6:
.LBB0_427:
	ds_read_b128 v[128:131], v201
	ds_read_b128 v[132:135], v201 offset:1024
	ds_read_b128 v[136:139], v201 offset:2048
	ds_read_b128 v[140:143], v201 offset:3072
	ds_read_b128 v[144:147], v202
	ds_read_b128 v[148:151], v202 offset:1024
	ds_read_b128 v[170:173], v202 offset:2048
	ds_read_b128 v[174:177], v202 offset:3072
	s_add_u32 s42, s40, 0xfff00080
	s_addc_u32 s43, s41, -1
	s_cmp_eq_u32 s63, 60
	s_cselect_b32 s45, s31, s43
	s_cselect_b32 s44, s39, s42
	s_cselect_b32 s43, s23, s62
	s_cselect_b32 s42, s60, s61
	v_lshl_add_u64 v[218:219], s[40:41], 0, v[162:163]
	s_add_i32 m0, s47, 0xc000
	ds_read_b128 v[178:181], v203
	ds_read_b128 v[182:185], v203 offset:1024
	ds_read_b128 v[186:189], v203 offset:2048
	ds_read_b128 v[190:193], v203 offset:3072
	ds_read_b128 v[194:197], v203 offset:4096
	ds_read_b128 v[206:209], v203 offset:5120
	ds_read_b128 v[210:213], v203 offset:6144
	ds_read_b128 v[214:217], v203 offset:7168
	global_load_lds_dwordx4 v[218:219], off
	v_lshl_add_u64 v[218:219], s[40:41], 0, v[164:165]
	s_add_i32 m0, s47, 0xe000
	s_nop 0
	global_load_lds_dwordx4 v[218:219], off
	s_waitcnt vmcnt(8)
	s_waitcnt lgkmcnt(0)
	s_barrier
	s_setprio 1
	s_waitcnt lgkmcnt(0)
	v_mfma_f32_16x16x32_bf16 v[124:127], v[128:131], v[178:181], v[124:127]
	v_mfma_f32_16x16x32_bf16 v[120:123], v[136:139], v[178:181], v[120:123]
	v_mfma_f32_16x16x32_bf16 v[108:111], v[128:131], v[186:189], v[108:111]
	v_mfma_f32_16x16x32_bf16 v[104:107], v[136:139], v[186:189], v[104:107]
	v_mfma_f32_16x16x32_bf16 v[92:95], v[128:131], v[194:197], v[92:95]
	v_mfma_f32_16x16x32_bf16 v[88:91], v[136:139], v[194:197], v[88:91]
	v_mfma_f32_16x16x32_bf16 v[76:79], v[128:131], v[210:213], v[76:79]
	v_mfma_f32_16x16x32_bf16 v[72:75], v[136:139], v[210:213], v[72:75]
	v_mfma_f32_16x16x32_bf16 v[124:127], v[132:135], v[182:185], v[124:127]
	v_mfma_f32_16x16x32_bf16 v[120:123], v[140:143], v[182:185], v[120:123]
	v_mfma_f32_16x16x32_bf16 v[108:111], v[132:135], v[190:193], v[108:111]
	v_mfma_f32_16x16x32_bf16 v[104:107], v[140:143], v[190:193], v[104:107]
	v_mfma_f32_16x16x32_bf16 v[92:95], v[132:135], v[206:209], v[92:95]
	v_mfma_f32_16x16x32_bf16 v[88:91], v[140:143], v[206:209], v[88:91]
	v_mfma_f32_16x16x32_bf16 v[76:79], v[132:135], v[214:217], v[76:79]
	v_mfma_f32_16x16x32_bf16 v[72:75], v[140:143], v[214:217], v[72:75]
	v_mfma_f32_16x16x32_bf16 v[116:119], v[144:147], v[178:181], v[116:119]
	v_mfma_f32_16x16x32_bf16 v[112:115], v[170:173], v[178:181], v[112:115]
	v_mfma_f32_16x16x32_bf16 v[100:103], v[144:147], v[186:189], v[100:103]
	v_mfma_f32_16x16x32_bf16 v[96:99], v[170:173], v[186:189], v[96:99]
	v_mfma_f32_16x16x32_bf16 v[84:87], v[144:147], v[194:197], v[84:87]
	v_mfma_f32_16x16x32_bf16 v[80:83], v[170:173], v[194:197], v[80:83]
	v_mfma_f32_16x16x32_bf16 v[68:71], v[144:147], v[210:213], v[68:71]
	v_mfma_f32_16x16x32_bf16 v[64:67], v[170:173], v[210:213], v[64:67]
	v_mfma_f32_16x16x32_bf16 v[116:119], v[148:151], v[182:185], v[116:119]
	v_mfma_f32_16x16x32_bf16 v[112:115], v[174:177], v[182:185], v[112:115]
	v_mfma_f32_16x16x32_bf16 v[100:103], v[148:151], v[190:193], v[100:103]
	v_mfma_f32_16x16x32_bf16 v[96:99], v[174:177], v[190:193], v[96:99]
	v_mfma_f32_16x16x32_bf16 v[84:87], v[148:151], v[206:209], v[84:87]
	v_mfma_f32_16x16x32_bf16 v[80:83], v[174:177], v[206:209], v[80:83]
	v_mfma_f32_16x16x32_bf16 v[68:71], v[148:151], v[214:217], v[68:71]
	v_mfma_f32_16x16x32_bf16 v[64:67], v[174:177], v[214:217], v[64:67]
	s_setprio 0
	s_barrier
	s_add_i32 s64, s57, s46
	v_lshl_add_u64 v[218:219], s[42:43], 0, v[154:155]
	s_mov_b32 m0, s64
	ds_read_b128 v[178:181], v203 offset:16384
	ds_read_b128 v[182:185], v203 offset:17408
	ds_read_b128 v[186:189], v203 offset:18432
	ds_read_b128 v[190:193], v203 offset:19456
	ds_read_b128 v[194:197], v203 offset:20480
	ds_read_b128 v[206:209], v203 offset:21504
	ds_read_b128 v[210:213], v203 offset:22528
	ds_read_b128 v[214:217], v203 offset:23552
	global_load_lds_dwordx4 v[218:219], off
	s_add_i32 m0, s64, 0x2000
	s_add_u32 s64, s42, 0x100000
	v_lshl_add_u64 v[220:221], s[42:43], 0, v[158:159]
	s_addc_u32 s65, s43, 0
	s_add_i32 s66, s58, s46
	global_load_lds_dwordx4 v[220:221], off
	v_lshl_add_u64 v[222:223], s[64:65], 0, v[154:155]
	s_mov_b32 m0, s66
	v_lshl_add_u64 v[224:225], s[44:45], 0, v[156:157]
	global_load_lds_dwordx4 v[222:223], off
	v_lshl_add_u64 v[222:223], s[64:65], 0, v[158:159]
	s_add_i32 m0, s66, 0x2000
	s_nop 0
	global_load_lds_dwordx4 v[222:223], off
	v_lshl_add_u64 v[222:223], s[44:45], 0, v[152:153]
	s_mov_b32 m0, s47
	s_nop 0
	global_load_lds_dwordx4 v[222:223], off
	s_mov_b32 m0, s48
	s_nop 0
	global_load_lds_dwordx4 v[224:225], off
	s_waitcnt vmcnt(8)
	s_waitcnt lgkmcnt(0)
	s_barrier
; #define PG8_STAGE(bufoff, gbase, voff) do { _Pragma("unroll") for (int _i = 0; _i < 2; ++_i) { unsigned vo_ = (voff)[_i]; if constexpr (FP8) asm volatile("" : "+v"(vo_)); \
;         __builtin_amdgcn_global_load_lds((const unsigned*)((const char*)(gbase) + vo_), (PG8_LAS unsigned*)(lds + (bufoff) + ldsw + _i * 8192), 16, 0, 0); } } while (0)
; #define PG8_LDA(dst, b, h) do { _Pragma("unroll") for (int m = 0; m < 4; ++m) _Pragma("unroll") for (int k = 0; k < 2; ++k) dst[m][k] = *(const PG8_LAS bf16x8*)(lds + PG8_SA(b, h) + aoff + m * 2048 + k * 1024); } while (0)
; #define PG8_LDB(dst, b, h) do { _Pragma("unroll") for (int n = 0; n < 2; ++n) _Pragma("unroll") for (int k = 0; k < 2; ++k) dst[n][k] = *(const PG8_LAS bf16x8*)(lds + PG8_SB(b, h) + boff + n * 2048 + k * 1024); } while (0)
; #define PG8_WAIT_V(n) asm volatile("s_waitcnt vmcnt(" #n ")" ::: "memory")
; #define PG8_WAIT_L(n) asm volatile("s_waitcnt lgkmcnt(" #n ")" ::: "memory")
; #define PG8_BAR __builtin_amdgcn_s_barrier()
; #define PG8_SCHED __builtin_amdgcn_sched_barrier(0)
; template <class Epi, class Sched, bool ALIGN_EPI = false, bool SP2 = false, bool FP8 = false>
; __device__ __forceinline__ void gemm_phase(PG8_LAS unsigned char* lds, const Gemm g, const Sched& S, const Epi& E) {
;     ...
;             PG8_WAIT_V(8); PG8_WAIT_L(0); PG8_BAR; PG8_MMA(1, 0, At, B0); PG8_MMA(1, 1, At, B1); PG8_BAR; PG8_SCHED;
;             PG8_LDB(B0, 1, 0); PG8_LDB(B1, 1, 1); PG8_SCHED; PG8_LDA(At, 1, 0); PG8_STAGE(PG8_SA(0, 1), a2 + hstep, voffA);
;             PG8_WAIT_V(8); PG8_WAIT_L(0); PG8_BAR; PG8_MMA(0, 0, At, B0); PG8_MMA(0, 1, At, B1); PG8_BAR; PG8_SCHED;
	s_setprio 1
	s_waitcnt lgkmcnt(0)
	v_mfma_f32_16x16x32_bf16 v[60:63], v[128:131], v[178:181], v[60:63]
	v_mfma_f32_16x16x32_bf16 v[56:59], v[136:139], v[178:181], v[56:59]
	v_mfma_f32_16x16x32_bf16 v[44:47], v[128:131], v[186:189], v[44:47]
	v_mfma_f32_16x16x32_bf16 v[40:43], v[136:139], v[186:189], v[40:43]
	v_mfma_f32_16x16x32_bf16 v[28:31], v[128:131], v[194:197], v[28:31]
	v_mfma_f32_16x16x32_bf16 v[24:27], v[136:139], v[194:197], v[24:27]
	v_mfma_f32_16x16x32_bf16 v[12:15], v[128:131], v[210:213], v[12:15]
	v_mfma_f32_16x16x32_bf16 v[8:11], v[136:139], v[210:213], v[8:11]
	v_mfma_f32_16x16x32_bf16 v[60:63], v[132:135], v[182:185], v[60:63]
	v_mfma_f32_16x16x32_bf16 v[56:59], v[140:143], v[182:185], v[56:59]
	v_mfma_f32_16x16x32_bf16 v[44:47], v[132:135], v[190:193], v[44:47]
	v_mfma_f32_16x16x32_bf16 v[40:43], v[140:143], v[190:193], v[40:43]
	v_mfma_f32_16x16x32_bf16 v[28:31], v[132:135], v[206:209], v[28:31]
	v_mfma_f32_16x16x32_bf16 v[24:27], v[140:143], v[206:209], v[24:27]
	v_mfma_f32_16x16x32_bf16 v[12:15], v[132:135], v[214:217], v[12:15]
	v_mfma_f32_16x16x32_bf16 v[8:11], v[140:143], v[214:217], v[8:11]
	v_mfma_f32_16x16x32_bf16 v[52:55], v[144:147], v[178:181], v[52:55]
	v_mfma_f32_16x16x32_bf16 v[48:51], v[170:173], v[178:181], v[48:51]
	v_mfma_f32_16x16x32_bf16 v[36:39], v[144:147], v[186:189], v[36:39]
	v_mfma_f32_16x16x32_bf16 v[32:35], v[170:173], v[186:189], v[32:35]
	v_mfma_f32_16x16x32_bf16 v[20:23], v[144:147], v[194:197], v[20:23]
	v_mfma_f32_16x16x32_bf16 v[16:19], v[170:173], v[194:197], v[16:19]
	v_mfma_f32_16x16x32_bf16 v[4:7], v[144:147], v[210:213], v[4:7]
	v_mfma_f32_16x16x32_bf16 v[0:3], v[170:173], v[210:213], v[0:3]
	v_mfma_f32_16x16x32_bf16 v[52:55], v[148:151], v[182:185], v[52:55]
	v_mfma_f32_16x16x32_bf16 v[48:51], v[174:177], v[182:185], v[48:51]
	v_mfma_f32_16x16x32_bf16 v[36:39], v[148:151], v[190:193], v[36:39]
	v_mfma_f32_16x16x32_bf16 v[32:35], v[174:177], v[190:193], v[32:35]
	v_mfma_f32_16x16x32_bf16 v[20:23], v[148:151], v[206:209], v[20:23]
	v_mfma_f32_16x16x32_bf16 v[16:19], v[174:177], v[206:209], v[16:19]
	v_mfma_f32_16x16x32_bf16 v[4:7], v[148:151], v[214:217], v[4:7]
	v_mfma_f32_16x16x32_bf16 v[0:3], v[174:177], v[214:217], v[0:3]
	s_setprio 0
	s_barrier
	s_add_i32 s64, 0, 0x18000
	s_add_i32 s65, 0, 0x1c000
	v_add_u32_e32 v140, s64, v199
	v_add_u32_e32 v174, s65, v199
	ds_read_b128 v[128:131], v140
	ds_read_b128 v[132:135], v140 offset:1024
	ds_read_b128 v[136:139], v140 offset:2048
	ds_read_b128 v[140:143], v140 offset:3072
	ds_read_b128 v[144:147], v174
	ds_read_b128 v[148:151], v174 offset:1024
	ds_read_b128 v[170:173], v174 offset:2048
	ds_read_b128 v[174:177], v174 offset:3072
	s_add_u32 s44, s44, 0x100000
	s_addc_u32 s45, s45, 0
	s_mov_b32 m0, s49
	v_lshl_add_u64 v[226:227], s[44:45], 0, v[152:153]
	ds_read_b128 v[178:181], v203 offset:32768
	ds_read_b128 v[182:185], v203 offset:33792
	ds_read_b128 v[186:189], v203 offset:34816
	ds_read_b128 v[190:193], v203 offset:35840
	ds_read_b128 v[194:197], v203 offset:36864
	ds_read_b128 v[206:209], v203 offset:37888
	ds_read_b128 v[210:213], v203 offset:38912
	ds_read_b128 v[214:217], v203 offset:39936
	global_load_lds_dwordx4 v[226:227], off
	v_lshl_add_u64 v[226:227], s[44:45], 0, v[156:157]
	s_mov_b32 m0, s50
	s_nop 0
	global_load_lds_dwordx4 v[226:227], off
	s_waitcnt vmcnt(8)
	s_waitcnt lgkmcnt(0)
	s_barrier
	s_setprio 1
	s_waitcnt lgkmcnt(0)
	v_mfma_f32_16x16x32_bf16 v[124:127], v[128:131], v[178:181], v[124:127]
	v_mfma_f32_16x16x32_bf16 v[120:123], v[136:139], v[178:181], v[120:123]
	v_mfma_f32_16x16x32_bf16 v[108:111], v[128:131], v[186:189], v[108:111]
	v_mfma_f32_16x16x32_bf16 v[104:107], v[136:139], v[186:189], v[104:107]
	v_mfma_f32_16x16x32_bf16 v[92:95], v[128:131], v[194:197], v[92:95]
	v_mfma_f32_16x16x32_bf16 v[88:91], v[136:139], v[194:197], v[88:91]
	v_mfma_f32_16x16x32_bf16 v[76:79], v[128:131], v[210:213], v[76:79]
	v_mfma_f32_16x16x32_bf16 v[72:75], v[136:139], v[210:213], v[72:75]
	v_mfma_f32_16x16x32_bf16 v[124:127], v[132:135], v[182:185], v[124:127]
	v_mfma_f32_16x16x32_bf16 v[120:123], v[140:143], v[182:185], v[120:123]
	v_mfma_f32_16x16x32_bf16 v[108:111], v[132:135], v[190:193], v[108:111]
	v_mfma_f32_16x16x32_bf16 v[104:107], v[140:143], v[190:193], v[104:107]
	v_mfma_f32_16x16x32_bf16 v[92:95], v[132:135], v[206:209], v[92:95]
	v_mfma_f32_16x16x32_bf16 v[88:91], v[140:143], v[206:209], v[88:91]
	v_mfma_f32_16x16x32_bf16 v[76:79], v[132:135], v[214:217], v[76:79]
	v_mfma_f32_16x16x32_bf16 v[72:75], v[140:143], v[214:217], v[72:75]
	v_mfma_f32_16x16x32_bf16 v[116:119], v[144:147], v[178:181], v[116:119]
	v_mfma_f32_16x16x32_bf16 v[112:115], v[170:173], v[178:181], v[112:115]
	v_mfma_f32_16x16x32_bf16 v[100:103], v[144:147], v[186:189], v[100:103]
	v_mfma_f32_16x16x32_bf16 v[96:99], v[170:173], v[186:189], v[96:99]
	v_mfma_f32_16x16x32_bf16 v[84:87], v[144:147], v[194:197], v[84:87]
	v_mfma_f32_16x16x32_bf16 v[80:83], v[170:173], v[194:197], v[80:83]
	v_mfma_f32_16x16x32_bf16 v[68:71], v[144:147], v[210:213], v[68:71]
	v_mfma_f32_16x16x32_bf16 v[64:67], v[170:173], v[210:213], v[64:67]
	v_mfma_f32_16x16x32_bf16 v[116:119], v[148:151], v[182:185], v[116:119]
	v_mfma_f32_16x16x32_bf16 v[112:115], v[174:177], v[182:185], v[112:115]
	v_mfma_f32_16x16x32_bf16 v[100:103], v[148:151], v[190:193], v[100:103]
	v_mfma_f32_16x16x32_bf16 v[96:99], v[174:177], v[190:193], v[96:99]
	v_mfma_f32_16x16x32_bf16 v[84:87], v[148:151], v[206:209], v[84:87]
	v_mfma_f32_16x16x32_bf16 v[80:83], v[174:177], v[206:209], v[80:83]
	v_mfma_f32_16x16x32_bf16 v[68:71], v[148:151], v[214:217], v[68:71]
	v_mfma_f32_16x16x32_bf16 v[64:67], v[174:177], v[214:217], v[64:67]
	s_setprio 0
	s_barrier
; #define PG8_STAGE(bufoff, gbase, voff) do { _Pragma("unroll") for (int _i = 0; _i < 2; ++_i) { unsigned vo_ = (voff)[_i]; if constexpr (FP8) asm volatile("" : "+v"(vo_)); \
;         __builtin_amdgcn_global_load_lds((const unsigned*)((const char*)(gbase) + vo_), (PG8_LAS unsigned*)(lds + (bufoff) + ldsw + _i * 8192), 16, 0, 0); } } while (0)
; #define PG8_LDA(dst, b, h) do { _Pragma("unroll") for (int m = 0; m < 4; ++m) _Pragma("unroll") for (int k = 0; k < 2; ++k) dst[m][k] = *(const PG8_LAS bf16x8*)(lds + PG8_SA(b, h) + aoff + m * 2048 + k * 1024); } while (0)
; #define PG8_WAIT_V(n) asm volatile("s_waitcnt vmcnt(" #n ")" ::: "memory")
; #define PG8_WAIT_L(n) asm volatile("s_waitcnt lgkmcnt(" #n ")" ::: "memory")
; #define PG8_BAR __builtin_amdgcn_s_barrier()
; #define PG8_SCHED __builtin_amdgcn_sched_barrier(0)
; template <class Epi, class Sched, bool ALIGN_EPI = false, bool SP2 = false, bool FP8 = false>
; __device__ __forceinline__ void gemm_phase(PG8_LAS unsigned char* lds, const Gemm g, const Sched& S, const Epi& E) {
;     ...
;             PG8_LDA(At, 1, 1); PG8_STAGE(PG8_SB(1, 0), b3, voffB); PG8_STAGE(PG8_SB(1, 1), b3 + hstep, voffB); PG8_STAGE(PG8_SA(1, 0), a3, voffA);
;             PG8_WAIT_V(8); PG8_WAIT_L(0); PG8_BAR; PG8_MMA(1, 0, At, B0); PG8_MMA(1, 1, At, B1); PG8_BAR; PG8_SCHED;
	s_add_i32 s44, s64, s46
	v_lshl_add_u64 v[218:219], v[218:219], 0, s[12:13]
	s_mov_b32 m0, s44
	ds_read_b128 v[178:181], v203 offset:49152
	ds_read_b128 v[182:185], v203 offset:50176
	ds_read_b128 v[186:189], v203 offset:51200
	ds_read_b128 v[190:193], v203 offset:52224
	ds_read_b128 v[194:197], v203 offset:53248
	ds_read_b128 v[206:209], v203 offset:54272
	ds_read_b128 v[210:213], v203 offset:55296
	ds_read_b128 v[214:217], v203 offset:56320
	global_load_lds_dwordx4 v[218:219], off
	s_add_i32 m0, s44, 0x2000
	s_add_u32 s42, s42, 0x100080
	v_lshl_add_u64 v[218:219], v[220:221], 0, s[12:13]
	s_addc_u32 s43, s43, 0
	s_add_i32 s44, s65, s46
	global_load_lds_dwordx4 v[218:219], off
	v_lshl_add_u64 v[218:219], s[42:43], 0, v[154:155]
	s_mov_b32 m0, s44
	s_nop 0
	global_load_lds_dwordx4 v[218:219], off
	v_lshl_add_u64 v[218:219], s[42:43], 0, v[158:159]
	s_add_i32 m0, s44, 0x2000
	s_nop 0
	global_load_lds_dwordx4 v[218:219], off
	v_lshl_add_u64 v[218:219], v[222:223], 0, s[12:13]
	s_mov_b32 m0, s54
	s_nop 0
	global_load_lds_dwordx4 v[218:219], off
	v_lshl_add_u64 v[218:219], v[224:225], 0, s[12:13]
	s_mov_b32 m0, s55
	s_nop 0
	global_load_lds_dwordx4 v[218:219], off
	s_waitcnt vmcnt(8)
	s_waitcnt lgkmcnt(0)
	s_barrier
	s_setprio 1
	s_waitcnt lgkmcnt(0)
	v_mfma_f32_16x16x32_bf16 v[60:63], v[128:131], v[178:181], v[60:63]
	v_mfma_f32_16x16x32_bf16 v[56:59], v[136:139], v[178:181], v[56:59]
	v_mfma_f32_16x16x32_bf16 v[44:47], v[128:131], v[186:189], v[44:47]
	v_mfma_f32_16x16x32_bf16 v[40:43], v[136:139], v[186:189], v[40:43]
	v_mfma_f32_16x16x32_bf16 v[28:31], v[128:131], v[194:197], v[28:31]
	v_mfma_f32_16x16x32_bf16 v[24:27], v[136:139], v[194:197], v[24:27]
	v_mfma_f32_16x16x32_bf16 v[12:15], v[128:131], v[210:213], v[12:15]
	v_mfma_f32_16x16x32_bf16 v[8:11], v[136:139], v[210:213], v[8:11]
	v_mfma_f32_16x16x32_bf16 v[60:63], v[132:135], v[182:185], v[60:63]
	v_mfma_f32_16x16x32_bf16 v[56:59], v[140:143], v[182:185], v[56:59]
	v_mfma_f32_16x16x32_bf16 v[44:47], v[132:135], v[190:193], v[44:47]
	v_mfma_f32_16x16x32_bf16 v[40:43], v[140:143], v[190:193], v[40:43]
	v_mfma_f32_16x16x32_bf16 v[28:31], v[132:135], v[206:209], v[28:31]
	v_mfma_f32_16x16x32_bf16 v[24:27], v[140:143], v[206:209], v[24:27]
	v_mfma_f32_16x16x32_bf16 v[12:15], v[132:135], v[214:217], v[12:15]
	v_mfma_f32_16x16x32_bf16 v[8:11], v[140:143], v[214:217], v[8:11]
	v_mfma_f32_16x16x32_bf16 v[52:55], v[144:147], v[178:181], v[52:55]
	v_mfma_f32_16x16x32_bf16 v[48:51], v[170:173], v[178:181], v[48:51]
	v_mfma_f32_16x16x32_bf16 v[36:39], v[144:147], v[186:189], v[36:39]
	v_mfma_f32_16x16x32_bf16 v[32:35], v[170:173], v[186:189], v[32:35]
	v_mfma_f32_16x16x32_bf16 v[20:23], v[144:147], v[194:197], v[20:23]
	v_mfma_f32_16x16x32_bf16 v[16:19], v[170:173], v[194:197], v[16:19]
	v_mfma_f32_16x16x32_bf16 v[4:7], v[144:147], v[210:213], v[4:7]
	v_mfma_f32_16x16x32_bf16 v[0:3], v[170:173], v[210:213], v[0:3]
	v_mfma_f32_16x16x32_bf16 v[52:55], v[148:151], v[182:185], v[52:55]
	v_mfma_f32_16x16x32_bf16 v[48:51], v[174:177], v[182:185], v[48:51]
	v_mfma_f32_16x16x32_bf16 v[36:39], v[148:151], v[190:193], v[36:39]
	v_mfma_f32_16x16x32_bf16 v[32:35], v[174:177], v[190:193], v[32:35]
	v_mfma_f32_16x16x32_bf16 v[20:23], v[148:151], v[206:209], v[20:23]
	v_mfma_f32_16x16x32_bf16 v[16:19], v[174:177], v[206:209], v[16:19]
	v_mfma_f32_16x16x32_bf16 v[4:7], v[148:151], v[214:217], v[4:7]
	v_mfma_f32_16x16x32_bf16 v[0:3], v[174:177], v[214:217], v[0:3]
	s_setprio 0
	s_barrier
	s_add_i32 s63, s63, 2
	s_add_u32 s40, s40, 0x100
	s_addc_u32 s41, s41, 0
	s_add_u32 s61, s61, 0x100
	s_addc_u32 s62, s62, 0
	s_cmp_gt_u32 s63, 61
	s_cbranch_scc0 .LBB0_427
	s_and_b64 vcc, exec, s[14:15]
	s_cbranch_vccz .LBB0_430
